# stack: BT1 table loads two-stage up front, attention Q prefetch + persistent tile 0, EpiGLU loads issued up front, P1 last-N-tile padding half skipped
# baseline (speedup 1.0000x reference)
.LBB0_259:
	s_add_u32 s14, s26, 0x7000000
	s_addc_u32 s15, s27, 0
	s_add_u32 s12, s26, 0x1b200000
	s_addc_u32 s13, s27, 0
	s_add_u32 s8, s26, 0x2c00000
	s_addc_u32 s9, s27, 0
	v_readlane_b32 s4, v236, 5
	s_cmp_lt_i32 s4, 2
	s_cselect_b64 s[20:21], -1, 0
	s_and_b64 s[0:1], s[0:1], s[20:21]
	s_andn2_b64 vcc, exec, s[0:1]
	v_readlane_b32 s5, v236, 6
	s_cbranch_vccnz .LBB0_350
	v_mov_b32_e32 v0, v191
	s_lshl_b32 s1, s2, 9
	v_readfirstlane_b32 s0, v0
	s_andn2_b32 s0, s0, 63
	s_add_i32 s0, s0, s1
	v_and_or_b32 v0, v0, 63, s0
	s_mov_b32 s0, 0x200000
	s_lshl_b32 s4, s30, 9
	v_cmp_gt_i32_e32 vcc, s0, v0
	v_lshlrev_b32_e32 v10, 1, v0
	s_and_saveexec_b64 s[0:1], vcc
	s_cbranch_execz .LBB0_265
	s_cmpk_lg_i32 s30, 0x100
	s_cbranch_scc1 .Lbt1_orig
	v_bfe_u32 v1, v0, 8, 8
	v_and_b32_e32 v2, 63, v1
	v_bfe_u32 v3, v0, 4, 4
	v_and_b32_e32 v4, 15, v0
	v_lshrrev_b32_e32 v5, 16, v0
	v_mul_u32_u24_e32 v6, 17, v5
	v_sub_u32_e32 v6, v6, v3
	v_lshlrev_b32_e32 v6, 7, v6
	v_lshl_add_u32 v6, v2, 1, v6
	v_add_u32_e32 v6, 0x780, v6
	v_lshlrev_b32_e32 v6, 2, v6
	v_lshl_add_u32 v7, v5, 6, v2
	v_lshlrev_b32_e32 v7, 7, v7
	v_lshl_add_u32 v7, v4, 3, v7
	s_add_u32 s6, s26, 0x1e400000
	s_addc_u32 s7, s27, 0
	s_add_u32 s10, s26, 0x1e444000
	s_addc_u32 s11, s27, 0
	s_add_u32 s28, s26, 0x1c90000
	s_addc_u32 s29, s27, 0
	s_movk_i32 s5, 0x80
	s_movk_i32 s41, 0x7fff
	v_cmp_gt_u32_e64 s[36:37], s5, v1
	v_cmp_gt_u32_e64 s[38:39], 64, v1
	s_mov_b64 s[42:43], exec
	s_and_b64 exec, exec, s[36:37]
	global_load_dwordx2 v[16:17], v6, s[6:7]
	global_load_dwordx2 v[18:19], v7, s[10:11]
	s_add_u32 s6, s6, 0x4400
	s_addc_u32 s7, s7, 0
	s_add_u32 s10, s10, 0x4000
	s_addc_u32 s11, s11, 0
	global_load_dwordx2 v[20:21], v6, s[6:7]
	global_load_dwordx2 v[22:23], v7, s[10:11]
	s_add_u32 s6, s6, 0x4400
	s_addc_u32 s7, s7, 0
	s_add_u32 s10, s10, 0x4000
	s_addc_u32 s11, s11, 0
	global_load_dwordx2 v[24:25], v6, s[6:7]
	global_load_dwordx2 v[26:27], v7, s[10:11]
	s_add_u32 s6, s6, 0x4400
	s_addc_u32 s7, s7, 0
	s_add_u32 s10, s10, 0x4000
	s_addc_u32 s11, s11, 0
	global_load_dwordx2 v[28:29], v6, s[6:7]
	global_load_dwordx2 v[30:31], v7, s[10:11]
	s_add_u32 s6, s6, 0x4400
	s_addc_u32 s7, s7, 0
	s_add_u32 s10, s10, 0x4000
	s_addc_u32 s11, s11, 0
	global_load_dwordx2 v[32:33], v6, s[6:7]
	global_load_dwordx2 v[34:35], v7, s[10:11]
	s_add_u32 s6, s6, 0x4400
	s_addc_u32 s7, s7, 0
	s_add_u32 s10, s10, 0x4000
	s_addc_u32 s11, s11, 0
	global_load_dwordx2 v[36:37], v6, s[6:7]
	global_load_dwordx2 v[38:39], v7, s[10:11]
	s_add_u32 s6, s6, 0x4400
	s_addc_u32 s7, s7, 0
	s_add_u32 s10, s10, 0x4000
	s_addc_u32 s11, s11, 0
	global_load_dwordx2 v[40:41], v6, s[6:7]
	global_load_dwordx2 v[42:43], v7, s[10:11]
	s_add_u32 s6, s6, 0x4400
	s_addc_u32 s7, s7, 0
	s_add_u32 s10, s10, 0x4000
	s_addc_u32 s11, s11, 0
	global_load_dwordx2 v[44:45], v6, s[6:7]
	global_load_dwordx2 v[46:47], v7, s[10:11]
	s_add_u32 s6, s6, 0x4400
	s_addc_u32 s7, s7, 0
	s_add_u32 s10, s10, 0x4000
	s_addc_u32 s11, s11, 0
	s_mov_b64 exec, s[42:43]
	s_waitcnt vmcnt(0)
	s_and_b64 exec, exec, s[36:37]
	global_load_dwordx2 v[48:49], v6, s[6:7]
	global_load_dwordx2 v[50:51], v7, s[10:11]
	s_add_u32 s6, s6, 0x4400
	s_addc_u32 s7, s7, 0
	s_add_u32 s10, s10, 0x4000
	s_addc_u32 s11, s11, 0
	global_load_dwordx2 v[52:53], v6, s[6:7]
	global_load_dwordx2 v[54:55], v7, s[10:11]
	s_add_u32 s6, s6, 0x4400
	s_addc_u32 s7, s7, 0
	s_add_u32 s10, s10, 0x4000
	s_addc_u32 s11, s11, 0
	global_load_dwordx2 v[56:57], v6, s[6:7]
	global_load_dwordx2 v[58:59], v7, s[10:11]
	s_add_u32 s6, s6, 0x4400
	s_addc_u32 s7, s7, 0
	s_add_u32 s10, s10, 0x4000
	s_addc_u32 s11, s11, 0
	global_load_dwordx2 v[60:61], v6, s[6:7]
	global_load_dwordx2 v[62:63], v7, s[10:11]
	s_add_u32 s6, s6, 0x4400
	s_addc_u32 s7, s7, 0
	s_add_u32 s10, s10, 0x4000
	s_addc_u32 s11, s11, 0
	global_load_dwordx2 v[64:65], v6, s[6:7]
	global_load_dwordx2 v[66:67], v7, s[10:11]
	s_add_u32 s6, s6, 0x4400
	s_addc_u32 s7, s7, 0
	s_add_u32 s10, s10, 0x4000
	s_addc_u32 s11, s11, 0
	global_load_dwordx2 v[68:69], v6, s[6:7]
	global_load_dwordx2 v[70:71], v7, s[10:11]
	s_add_u32 s6, s6, 0x4400
	s_addc_u32 s7, s7, 0
	s_add_u32 s10, s10, 0x4000
	s_addc_u32 s11, s11, 0
	global_load_dwordx2 v[72:73], v6, s[6:7]
	global_load_dwordx2 v[74:75], v7, s[10:11]
	s_add_u32 s6, s6, 0x4400
	s_addc_u32 s7, s7, 0
	s_add_u32 s10, s10, 0x4000
	s_addc_u32 s11, s11, 0
	global_load_dwordx2 v[76:77], v6, s[6:7]
	global_load_dwordx2 v[78:79], v7, s[10:11]
	s_add_u32 s6, s6, 0x4400
	s_addc_u32 s7, s7, 0
	s_add_u32 s10, s10, 0x4000
	s_addc_u32 s11, s11, 0
	s_mov_b64 exec, s[42:43]
	v_pk_mul_f32 v[80:81], v[16:17], v[18:19]
	v_pk_mul_f32 v[82:83], v[16:17], v[18:19] op_sel:[1,0] op_sel_hi:[0,1]
	v_sub_f32_e32 v80, v80, v81
	v_add_f32_e32 v82, v82, v83
	v_cndmask_b32_e64 v80, v82, v80, s[38:39]
	v_cndmask_b32_e64 v80, 0, v80, s[36:37]
	v_bfe_u32 v81, v80, 16, 1
	v_add3_u32 v80, v80, v81, s41
	global_store_short_d16_hi v10, v80, s[28:29]
	s_add_u32 s28, s28, 0x40000
	s_addc_u32 s29, s29, 0
	v_pk_mul_f32 v[84:85], v[20:21], v[22:23]
	v_pk_mul_f32 v[86:87], v[20:21], v[22:23] op_sel:[1,0] op_sel_hi:[0,1]
	v_sub_f32_e32 v84, v84, v85
	v_add_f32_e32 v86, v86, v87
	v_cndmask_b32_e64 v84, v86, v84, s[38:39]
	v_cndmask_b32_e64 v84, 0, v84, s[36:37]
	v_bfe_u32 v85, v84, 16, 1
	v_add3_u32 v84, v84, v85, s41
	global_store_short_d16_hi v10, v84, s[28:29]
	s_add_u32 s28, s28, 0x40000
	s_addc_u32 s29, s29, 0
	v_pk_mul_f32 v[80:81], v[24:25], v[26:27]
	v_pk_mul_f32 v[82:83], v[24:25], v[26:27] op_sel:[1,0] op_sel_hi:[0,1]
	v_sub_f32_e32 v80, v80, v81
	v_add_f32_e32 v82, v82, v83
	v_cndmask_b32_e64 v80, v82, v80, s[38:39]
	v_cndmask_b32_e64 v80, 0, v80, s[36:37]
	v_bfe_u32 v81, v80, 16, 1
	v_add3_u32 v80, v80, v81, s41
	global_store_short_d16_hi v10, v80, s[28:29]
	s_add_u32 s28, s28, 0x40000
	s_addc_u32 s29, s29, 0
	v_pk_mul_f32 v[84:85], v[28:29], v[30:31]
	v_pk_mul_f32 v[86:87], v[28:29], v[30:31] op_sel:[1,0] op_sel_hi:[0,1]
	v_sub_f32_e32 v84, v84, v85
	v_add_f32_e32 v86, v86, v87
	v_cndmask_b32_e64 v84, v86, v84, s[38:39]
	v_cndmask_b32_e64 v84, 0, v84, s[36:37]
	v_bfe_u32 v85, v84, 16, 1
	v_add3_u32 v84, v84, v85, s41
	global_store_short_d16_hi v10, v84, s[28:29]
	s_add_u32 s28, s28, 0x40000
	s_addc_u32 s29, s29, 0
	v_pk_mul_f32 v[80:81], v[32:33], v[34:35]
	v_pk_mul_f32 v[82:83], v[32:33], v[34:35] op_sel:[1,0] op_sel_hi:[0,1]
	v_sub_f32_e32 v80, v80, v81
	v_add_f32_e32 v82, v82, v83
	v_cndmask_b32_e64 v80, v82, v80, s[38:39]
	v_cndmask_b32_e64 v80, 0, v80, s[36:37]
	v_bfe_u32 v81, v80, 16, 1
	v_add3_u32 v80, v80, v81, s41
	global_store_short_d16_hi v10, v80, s[28:29]
	s_add_u32 s28, s28, 0x40000
	s_addc_u32 s29, s29, 0
	v_pk_mul_f32 v[84:85], v[36:37], v[38:39]
	v_pk_mul_f32 v[86:87], v[36:37], v[38:39] op_sel:[1,0] op_sel_hi:[0,1]
	v_sub_f32_e32 v84, v84, v85
	v_add_f32_e32 v86, v86, v87
	v_cndmask_b32_e64 v84, v86, v84, s[38:39]
	v_cndmask_b32_e64 v84, 0, v84, s[36:37]
	v_bfe_u32 v85, v84, 16, 1
	v_add3_u32 v84, v84, v85, s41
	global_store_short_d16_hi v10, v84, s[28:29]
	s_add_u32 s28, s28, 0x40000
	s_addc_u32 s29, s29, 0
	v_pk_mul_f32 v[80:81], v[40:41], v[42:43]
	v_pk_mul_f32 v[82:83], v[40:41], v[42:43] op_sel:[1,0] op_sel_hi:[0,1]
	v_sub_f32_e32 v80, v80, v81
	v_add_f32_e32 v82, v82, v83
	v_cndmask_b32_e64 v80, v82, v80, s[38:39]
	v_cndmask_b32_e64 v80, 0, v80, s[36:37]
	v_bfe_u32 v81, v80, 16, 1
	v_add3_u32 v80, v80, v81, s41
	global_store_short_d16_hi v10, v80, s[28:29]
	s_add_u32 s28, s28, 0x40000
	s_addc_u32 s29, s29, 0
	v_pk_mul_f32 v[84:85], v[44:45], v[46:47]
	v_pk_mul_f32 v[86:87], v[44:45], v[46:47] op_sel:[1,0] op_sel_hi:[0,1]
	v_sub_f32_e32 v84, v84, v85
	v_add_f32_e32 v86, v86, v87
	v_cndmask_b32_e64 v84, v86, v84, s[38:39]
	v_cndmask_b32_e64 v84, 0, v84, s[36:37]
	v_bfe_u32 v85, v84, 16, 1
	v_add3_u32 v84, v84, v85, s41
	global_store_short_d16_hi v10, v84, s[28:29]
	s_add_u32 s28, s28, 0x40000
	s_addc_u32 s29, s29, 0
	s_waitcnt vmcnt(0)
	v_pk_mul_f32 v[80:81], v[48:49], v[50:51]
	v_pk_mul_f32 v[82:83], v[48:49], v[50:51] op_sel:[1,0] op_sel_hi:[0,1]
	v_sub_f32_e32 v80, v80, v81
	v_add_f32_e32 v82, v82, v83
	v_cndmask_b32_e64 v80, v82, v80, s[38:39]
	v_cndmask_b32_e64 v80, 0, v80, s[36:37]
	v_bfe_u32 v81, v80, 16, 1
	v_add3_u32 v80, v80, v81, s41
	global_store_short_d16_hi v10, v80, s[28:29]
	s_add_u32 s28, s28, 0x40000
	s_addc_u32 s29, s29, 0
	v_pk_mul_f32 v[84:85], v[52:53], v[54:55]
	v_pk_mul_f32 v[86:87], v[52:53], v[54:55] op_sel:[1,0] op_sel_hi:[0,1]
	v_sub_f32_e32 v84, v84, v85
	v_add_f32_e32 v86, v86, v87
	v_cndmask_b32_e64 v84, v86, v84, s[38:39]
	v_cndmask_b32_e64 v84, 0, v84, s[36:37]
	v_bfe_u32 v85, v84, 16, 1
	v_add3_u32 v84, v84, v85, s41
	global_store_short_d16_hi v10, v84, s[28:29]
	s_add_u32 s28, s28, 0x40000
	s_addc_u32 s29, s29, 0
	v_pk_mul_f32 v[80:81], v[56:57], v[58:59]
	v_pk_mul_f32 v[82:83], v[56:57], v[58:59] op_sel:[1,0] op_sel_hi:[0,1]
	v_sub_f32_e32 v80, v80, v81
	v_add_f32_e32 v82, v82, v83
	v_cndmask_b32_e64 v80, v82, v80, s[38:39]
	v_cndmask_b32_e64 v80, 0, v80, s[36:37]
	v_bfe_u32 v81, v80, 16, 1
	v_add3_u32 v80, v80, v81, s41
	global_store_short_d16_hi v10, v80, s[28:29]
	s_add_u32 s28, s28, 0x40000
	s_addc_u32 s29, s29, 0
	v_pk_mul_f32 v[84:85], v[60:61], v[62:63]
	v_pk_mul_f32 v[86:87], v[60:61], v[62:63] op_sel:[1,0] op_sel_hi:[0,1]
	v_sub_f32_e32 v84, v84, v85
	v_add_f32_e32 v86, v86, v87
	v_cndmask_b32_e64 v84, v86, v84, s[38:39]
	v_cndmask_b32_e64 v84, 0, v84, s[36:37]
	v_bfe_u32 v85, v84, 16, 1
	v_add3_u32 v84, v84, v85, s41
	global_store_short_d16_hi v10, v84, s[28:29]
	s_add_u32 s28, s28, 0x40000
	s_addc_u32 s29, s29, 0
	v_pk_mul_f32 v[80:81], v[64:65], v[66:67]
	v_pk_mul_f32 v[82:83], v[64:65], v[66:67] op_sel:[1,0] op_sel_hi:[0,1]
	v_sub_f32_e32 v80, v80, v81
	v_add_f32_e32 v82, v82, v83
	v_cndmask_b32_e64 v80, v82, v80, s[38:39]
	v_cndmask_b32_e64 v80, 0, v80, s[36:37]
	v_bfe_u32 v81, v80, 16, 1
	v_add3_u32 v80, v80, v81, s41
	global_store_short_d16_hi v10, v80, s[28:29]
	s_add_u32 s28, s28, 0x40000
	s_addc_u32 s29, s29, 0
	v_pk_mul_f32 v[84:85], v[68:69], v[70:71]
	v_pk_mul_f32 v[86:87], v[68:69], v[70:71] op_sel:[1,0] op_sel_hi:[0,1]
	v_sub_f32_e32 v84, v84, v85
	v_add_f32_e32 v86, v86, v87
	v_cndmask_b32_e64 v84, v86, v84, s[38:39]
	v_cndmask_b32_e64 v84, 0, v84, s[36:37]
	v_bfe_u32 v85, v84, 16, 1
	v_add3_u32 v84, v84, v85, s41
	global_store_short_d16_hi v10, v84, s[28:29]
	s_add_u32 s28, s28, 0x40000
	s_addc_u32 s29, s29, 0
	v_pk_mul_f32 v[80:81], v[72:73], v[74:75]
	v_pk_mul_f32 v[82:83], v[72:73], v[74:75] op_sel:[1,0] op_sel_hi:[0,1]
	v_sub_f32_e32 v80, v80, v81
	v_add_f32_e32 v82, v82, v83
	v_cndmask_b32_e64 v80, v82, v80, s[38:39]
	v_cndmask_b32_e64 v80, 0, v80, s[36:37]
	v_bfe_u32 v81, v80, 16, 1
	v_add3_u32 v80, v80, v81, s41
	global_store_short_d16_hi v10, v80, s[28:29]
	s_add_u32 s28, s28, 0x40000
	s_addc_u32 s29, s29, 0
	v_pk_mul_f32 v[84:85], v[76:77], v[78:79]
	v_pk_mul_f32 v[86:87], v[76:77], v[78:79] op_sel:[1,0] op_sel_hi:[0,1]
	v_sub_f32_e32 v84, v84, v85
	v_add_f32_e32 v86, v86, v87
	v_cndmask_b32_e64 v84, v86, v84, s[38:39]
	v_cndmask_b32_e64 v84, 0, v84, s[36:37]
	v_bfe_u32 v85, v84, 16, 1
	v_add3_u32 v84, v84, v85, s41
	global_store_short_d16_hi v10, v84, s[28:29]
	s_branch .LBB0_265
.Lbt1_orig:
	s_add_u32 s6, s26, 0x1e400000
	s_addc_u32 s7, s27, 0
	s_add_u32 s10, s26, 0x1e444000
	v_ashrrev_i32_e32 v1, 31, v0
	s_addc_u32 s11, s27, 0
	v_lshl_add_u64 v[2:3], v[0:1], 1, s[26:27]
	s_mov_b64 s[28:29], 0x1c90000
	s_ashr_i32 s5, s4, 31
	v_lshlrev_b32_e32 v6, 1, v0
	s_lshl_b32 s3, s30, 10
	v_lshl_add_u64 v[2:3], v[2:3], 0, s[28:29]
	s_lshl_b64 s[28:29], s[4:5], 1
	s_mov_b64 s[36:37], 0
	s_movk_i32 s5, 0x80
	v_mov_b32_e32 v5, 0
	s_movk_i32 s40, 0x7fff
	s_mov_b32 s41, 0x1fffff
	v_mov_b32_e32 v1, 64
	v_mov_b32_e32 v7, v0
	s_branch .LBB0_263

.LBB0_280:
	s_ashr_i32 s51, s50, 31
	s_lshl_b64 s[36:37], s[50:51], 19
	s_add_u32 s54, s52, s36
	s_addc_u32 s55, s53, s37
	s_ashr_i32 s49, s48, 31
	s_lshl_b64 s[36:37], s[48:49], 19
	s_add_u32 s58, s26, s36
	s_addc_u32 s59, s27, s37
	s_andn2_b64 vcc, exec, s[42:43]
	s_cbranch_vccnz .LBB0_348
	s_and_b64 s[36:37], s[4:5], exec
	s_cselect_b32 s7, s55, s11
	s_cselect_b32 s49, s54, s10
	s_cselect_b32 s51, s59, s29
	s_cselect_b32 s78, s58, s28
	s_add_u32 s10, s10, 0x40080
	s_addc_u32 s11, s11, 0
	s_add_u32 s79, s28, 0x100
	v_mov_b32_e32 v0, 0
	s_addc_u32 s84, s29, 0
	s_mov_b32 s28, 0
	v_mov_b32_e32 v1, v0
	v_mov_b32_e32 v2, v0
	v_mov_b32_e32 v3, v0
	v_mov_b32_e32 v4, v0
	v_mov_b32_e32 v5, v0
	v_mov_b32_e32 v6, v0
	v_mov_b32_e32 v7, v0
	v_mov_b32_e32 v8, v0
	v_mov_b32_e32 v9, v0
	v_mov_b32_e32 v10, v0
	v_mov_b32_e32 v11, v0
	v_mov_b32_e32 v12, v0
	v_mov_b32_e32 v13, v0
	v_mov_b32_e32 v14, v0
	v_mov_b32_e32 v15, v0
	v_mov_b32_e32 v16, v0
	v_mov_b32_e32 v17, v0
	v_mov_b32_e32 v18, v0
	v_mov_b32_e32 v19, v0
	v_mov_b32_e32 v20, v0
	v_mov_b32_e32 v21, v0
	v_mov_b32_e32 v22, v0
	v_mov_b32_e32 v23, v0
	v_mov_b32_e32 v24, v0
	v_mov_b32_e32 v25, v0
	v_mov_b32_e32 v26, v0
	v_mov_b32_e32 v27, v0
	v_mov_b32_e32 v28, v0
	v_mov_b32_e32 v29, v0
	v_mov_b32_e32 v30, v0
	v_mov_b32_e32 v31, v0
	v_mov_b32_e32 v64, v0
	s_waitcnt lgkmcnt(0)
	v_mov_b32_e32 v65, v0
	v_mov_b32_e32 v66, v0
	v_mov_b32_e32 v67, v0
	v_mov_b32_e32 v68, v0
	v_mov_b32_e32 v69, v0
	v_mov_b32_e32 v70, v0
	v_mov_b32_e32 v71, v0
	v_mov_b32_e32 v72, v0
	v_mov_b32_e32 v73, v0
	v_mov_b32_e32 v74, v0
	v_mov_b32_e32 v75, v0
	v_mov_b32_e32 v76, v0
	v_mov_b32_e32 v77, v0
	v_mov_b32_e32 v78, v0
	v_mov_b32_e32 v79, v0
	v_mov_b32_e32 v80, v0
	v_mov_b32_e32 v81, v0
	v_mov_b32_e32 v82, v0
	v_mov_b32_e32 v83, v0
	v_mov_b32_e32 v84, v0
	v_mov_b32_e32 v85, v0
	v_mov_b32_e32 v86, v0
	v_mov_b32_e32 v87, v0
	v_mov_b32_e32 v88, v0
	v_mov_b32_e32 v89, v0
	v_mov_b32_e32 v90, v0
	v_mov_b32_e32 v91, v0
	v_mov_b32_e32 v92, v0
	v_mov_b32_e32 v93, v0
	v_mov_b32_e32 v94, v0
	v_mov_b32_e32 v95, v0
	v_mov_b32_e32 v32, v0
	v_mov_b32_e32 v33, v0
	v_mov_b32_e32 v34, v0
	v_mov_b32_e32 v35, v0
	v_mov_b32_e32 v36, v0
	v_mov_b32_e32 v37, v0
	v_mov_b32_e32 v38, v0
	v_mov_b32_e32 v39, v0
	v_mov_b32_e32 v40, v0
	v_mov_b32_e32 v41, v0
	v_mov_b32_e32 v42, v0
	v_mov_b32_e32 v43, v0
	v_mov_b32_e32 v44, v0
	v_mov_b32_e32 v45, v0
	v_mov_b32_e32 v46, v0
	v_mov_b32_e32 v47, v0
	v_mov_b32_e32 v48, v0
	v_mov_b32_e32 v49, v0
	v_mov_b32_e32 v50, v0
	v_mov_b32_e32 v51, v0
	v_mov_b32_e32 v52, v0
	v_mov_b32_e32 v53, v0
	v_mov_b32_e32 v54, v0
	v_mov_b32_e32 v55, v0
	v_mov_b32_e32 v56, v0
	v_mov_b32_e32 v57, v0
	v_mov_b32_e32 v58, v0
	v_mov_b32_e32 v59, v0
	v_mov_b32_e32 v60, v0
	v_mov_b32_e32 v61, v0
	v_mov_b32_e32 v62, v0
	v_mov_b32_e32 v63, v0
	v_mov_b32_e32 v96, v0
	v_mov_b32_e32 v97, v0
	v_mov_b32_e32 v98, v0
	v_mov_b32_e32 v99, v0
	v_mov_b32_e32 v100, v0
	v_mov_b32_e32 v101, v0
	v_mov_b32_e32 v102, v0
	v_mov_b32_e32 v103, v0
	v_mov_b32_e32 v104, v0
	v_mov_b32_e32 v105, v0
	v_mov_b32_e32 v106, v0
	v_mov_b32_e32 v107, v0
	v_mov_b32_e32 v108, v0
	v_mov_b32_e32 v109, v0
	v_mov_b32_e32 v110, v0
	v_mov_b32_e32 v111, v0
	v_mov_b32_e32 v112, v0
	v_mov_b32_e32 v113, v0
	v_mov_b32_e32 v114, v0
	v_mov_b32_e32 v115, v0
	v_mov_b32_e32 v116, v0
	v_mov_b32_e32 v117, v0
	v_mov_b32_e32 v118, v0
	v_mov_b32_e32 v119, v0
	v_mov_b32_e32 v120, v0
	v_mov_b32_e32 v121, v0
	v_mov_b32_e32 v122, v0
	v_mov_b32_e32 v123, v0
	v_mov_b32_e32 v124, v0
	v_mov_b32_e32 v125, v0
	v_mov_b32_e32 v126, v0
	v_mov_b32_e32 v127, v0
	s_cmp_eq_u32 s0, 12
	s_cselect_b64 vcc, -1, 0
	s_andn2_b64 vcc, vcc, s[46:47]
.LBB0_282:
	ds_read_b128 v[128:131], v175
	ds_read_b128 v[132:135], v175 offset:1024
	ds_read_b128 v[154:157], v175 offset:2048
	ds_read_b128 v[158:161], v175 offset:3072
	ds_read_b128 v[162:165], v176
	ds_read_b128 v[166:169], v176 offset:1024
	ds_read_b128 v[170:173], v176 offset:2048
	ds_read_b128 v[180:183], v176 offset:3072
	s_add_i32 s85, s28, 2
	s_add_u32 s29, s10, 0xfffc0080
	s_addc_u32 s36, s11, -1
	s_cmp_eq_u32 s68, s28
	s_cselect_b32 s28, s78, s79
	s_cselect_b32 s37, s7, s36
	s_cselect_b32 s36, s49, s29
	s_cselect_b32 s29, s51, s84
	v_lshl_add_u64 v[188:189], s[10:11], 0, v[146:147]
	s_add_i32 m0, s57, 0xc000
	ds_read_b128 v[184:187], v177
	ds_read_b128 v[192:195], v177 offset:1024
	ds_read_b128 v[196:199], v177 offset:2048
	ds_read_b128 v[200:203], v177 offset:3072
	ds_read_b128 v[204:207], v177 offset:4096
	ds_read_b128 v[208:211], v177 offset:5120
	ds_read_b128 v[212:215], v177 offset:6144
	ds_read_b128 v[216:219], v177 offset:7168
	global_load_lds_dwordx4 v[188:189], off
	v_lshl_add_u64 v[188:189], s[10:11], 0, v[148:149]
	s_add_i32 m0, s57, 0xe000
	s_nop 0
	global_load_lds_dwordx4 v[188:189], off
	s_waitcnt vmcnt(8)
	s_waitcnt lgkmcnt(0)
	s_barrier
	s_setprio 1
	s_waitcnt lgkmcnt(0)
	v_mfma_f32_16x16x32_bf16 v[124:127], v[128:131], v[184:187], v[124:127]
	v_mfma_f32_16x16x32_bf16 v[120:123], v[154:157], v[184:187], v[120:123]
	v_mfma_f32_16x16x32_bf16 v[116:119], v[128:131], v[196:199], v[116:119]
	v_mfma_f32_16x16x32_bf16 v[112:115], v[154:157], v[196:199], v[112:115]
	v_mfma_f32_16x16x32_bf16 v[108:111], v[128:131], v[204:207], v[108:111]
	v_mfma_f32_16x16x32_bf16 v[104:107], v[154:157], v[204:207], v[104:107]
	v_mfma_f32_16x16x32_bf16 v[100:103], v[128:131], v[212:215], v[100:103]
	v_mfma_f32_16x16x32_bf16 v[96:99], v[154:157], v[212:215], v[96:99]
	v_mfma_f32_16x16x32_bf16 v[124:127], v[132:135], v[192:195], v[124:127]
	v_mfma_f32_16x16x32_bf16 v[120:123], v[158:161], v[192:195], v[120:123]
	v_mfma_f32_16x16x32_bf16 v[116:119], v[132:135], v[200:203], v[116:119]
	v_mfma_f32_16x16x32_bf16 v[112:115], v[158:161], v[200:203], v[112:115]
	v_mfma_f32_16x16x32_bf16 v[108:111], v[132:135], v[208:211], v[108:111]
	v_mfma_f32_16x16x32_bf16 v[104:107], v[158:161], v[208:211], v[104:107]
	v_mfma_f32_16x16x32_bf16 v[100:103], v[132:135], v[216:219], v[100:103]
	v_mfma_f32_16x16x32_bf16 v[96:99], v[158:161], v[216:219], v[96:99]
	s_setprio 0
	s_setprio 1
	s_cbranch_vccnz .Lp1skip0
	v_mfma_f32_16x16x32_bf16 v[60:63], v[162:165], v[184:187], v[60:63]
	v_mfma_f32_16x16x32_bf16 v[56:59], v[170:173], v[184:187], v[56:59]
	v_mfma_f32_16x16x32_bf16 v[52:55], v[162:165], v[196:199], v[52:55]
	v_mfma_f32_16x16x32_bf16 v[48:51], v[170:173], v[196:199], v[48:51]
	v_mfma_f32_16x16x32_bf16 v[44:47], v[162:165], v[204:207], v[44:47]
	v_mfma_f32_16x16x32_bf16 v[40:43], v[170:173], v[204:207], v[40:43]
	v_mfma_f32_16x16x32_bf16 v[36:39], v[162:165], v[212:215], v[36:39]
	v_mfma_f32_16x16x32_bf16 v[32:35], v[170:173], v[212:215], v[32:35]
	v_mfma_f32_16x16x32_bf16 v[60:63], v[166:169], v[192:195], v[60:63]
	v_mfma_f32_16x16x32_bf16 v[56:59], v[180:183], v[192:195], v[56:59]
	v_mfma_f32_16x16x32_bf16 v[52:55], v[166:169], v[200:203], v[52:55]
	v_mfma_f32_16x16x32_bf16 v[48:51], v[180:183], v[200:203], v[48:51]
	v_mfma_f32_16x16x32_bf16 v[44:47], v[166:169], v[208:211], v[44:47]
	v_mfma_f32_16x16x32_bf16 v[40:43], v[180:183], v[208:211], v[40:43]
	v_mfma_f32_16x16x32_bf16 v[36:39], v[166:169], v[216:219], v[36:39]
	v_mfma_f32_16x16x32_bf16 v[32:35], v[180:183], v[216:219], v[32:35]
.Lp1skip0:
	s_setprio 0
	s_barrier
	s_add_i32 s86, s72, s56
	s_mov_b32 m0, s86
	ds_read_b128 v[184:187], v177 offset:16384
	ds_read_b128 v[192:195], v177 offset:17408
	ds_read_b128 v[196:199], v177 offset:18432
	ds_read_b128 v[200:203], v177 offset:19456
	ds_read_b128 v[204:207], v177 offset:20480
	ds_read_b128 v[208:211], v177 offset:21504
	ds_read_b128 v[212:215], v177 offset:22528
	ds_read_b128 v[216:219], v177 offset:23552
	global_load_lds_dwordx4 v138, s[28:29]
	s_add_i32 m0, s86, 0x2000
	s_add_u32 s86, s28, 0x40000
	s_addc_u32 s87, s29, 0
	s_add_i32 s88, s73, s56
	global_load_lds_dwordx4 v142, s[28:29]
	s_mov_b32 m0, s88
	s_mov_b64 s[98:99], s[36:37]
	global_load_lds_dwordx4 v138, s[86:87]
	s_add_i32 m0, s88, 0x2000
	s_nop 0
	global_load_lds_dwordx4 v142, s[86:87]
	s_mov_b32 m0, s57
	s_nop 0
	global_load_lds_dwordx4 v136, s[36:37]
	s_mov_b32 m0, s60
	s_nop 0
	global_load_lds_dwordx4 v140, s[36:37]
	s_waitcnt vmcnt(8)
	s_waitcnt lgkmcnt(0)
	s_barrier
	s_setprio 1
	s_waitcnt lgkmcnt(0)
	v_mfma_f32_16x16x32_bf16 v[92:95], v[128:131], v[184:187], v[92:95]
	v_mfma_f32_16x16x32_bf16 v[88:91], v[154:157], v[184:187], v[88:91]
	v_mfma_f32_16x16x32_bf16 v[84:87], v[128:131], v[196:199], v[84:87]
	v_mfma_f32_16x16x32_bf16 v[80:83], v[154:157], v[196:199], v[80:83]
	v_mfma_f32_16x16x32_bf16 v[76:79], v[128:131], v[204:207], v[76:79]
	v_mfma_f32_16x16x32_bf16 v[72:75], v[154:157], v[204:207], v[72:75]
	v_mfma_f32_16x16x32_bf16 v[68:71], v[128:131], v[212:215], v[68:71]
	v_mfma_f32_16x16x32_bf16 v[64:67], v[154:157], v[212:215], v[64:67]
	v_mfma_f32_16x16x32_bf16 v[92:95], v[132:135], v[192:195], v[92:95]
	v_mfma_f32_16x16x32_bf16 v[88:91], v[158:161], v[192:195], v[88:91]
	v_mfma_f32_16x16x32_bf16 v[84:87], v[132:135], v[200:203], v[84:87]
	v_mfma_f32_16x16x32_bf16 v[80:83], v[158:161], v[200:203], v[80:83]
	v_mfma_f32_16x16x32_bf16 v[76:79], v[132:135], v[208:211], v[76:79]
	v_mfma_f32_16x16x32_bf16 v[72:75], v[158:161], v[208:211], v[72:75]
	v_mfma_f32_16x16x32_bf16 v[68:71], v[132:135], v[216:219], v[68:71]
	v_mfma_f32_16x16x32_bf16 v[64:67], v[158:161], v[216:219], v[64:67]
	s_setprio 0
	s_setprio 1
	s_cbranch_vccnz .Lp1skip1
	v_mfma_f32_16x16x32_bf16 v[28:31], v[162:165], v[184:187], v[28:31]
	v_mfma_f32_16x16x32_bf16 v[24:27], v[170:173], v[184:187], v[24:27]
	v_mfma_f32_16x16x32_bf16 v[20:23], v[162:165], v[196:199], v[20:23]
	v_mfma_f32_16x16x32_bf16 v[16:19], v[170:173], v[196:199], v[16:19]
	v_mfma_f32_16x16x32_bf16 v[12:15], v[162:165], v[204:207], v[12:15]
	v_mfma_f32_16x16x32_bf16 v[8:11], v[170:173], v[204:207], v[8:11]
	v_mfma_f32_16x16x32_bf16 v[4:7], v[162:165], v[212:215], v[4:7]
	v_mfma_f32_16x16x32_bf16 v[0:3], v[170:173], v[212:215], v[0:3]
	v_mfma_f32_16x16x32_bf16 v[28:31], v[166:169], v[192:195], v[28:31]
	v_mfma_f32_16x16x32_bf16 v[24:27], v[180:183], v[192:195], v[24:27]
	v_mfma_f32_16x16x32_bf16 v[20:23], v[166:169], v[200:203], v[20:23]
	v_mfma_f32_16x16x32_bf16 v[16:19], v[180:183], v[200:203], v[16:19]
	v_mfma_f32_16x16x32_bf16 v[12:15], v[166:169], v[208:211], v[12:15]
	v_mfma_f32_16x16x32_bf16 v[8:11], v[180:183], v[208:211], v[8:11]
	v_mfma_f32_16x16x32_bf16 v[4:7], v[166:169], v[216:219], v[4:7]
	v_mfma_f32_16x16x32_bf16 v[0:3], v[180:183], v[216:219], v[0:3]
.Lp1skip1:
	s_setprio 0
	s_barrier
	s_add_i32 s86, 0, 0x18000
	v_add_u32_e32 v144, s86, v174
	s_add_i32 s87, 0, 0x1c000
	ds_read_b128 v[128:131], v144
	ds_read_b128 v[132:135], v144 offset:1024
	ds_read_b128 v[154:157], v144 offset:2048
	ds_read_b128 v[158:161], v144 offset:3072
	v_add_u32_e32 v144, s87, v174
	ds_read_b128 v[162:165], v144
	ds_read_b128 v[166:169], v144 offset:1024
	ds_read_b128 v[170:173], v144 offset:2048
	ds_read_b128 v[180:183], v144 offset:3072
	s_add_u32 s36, s36, 0x40000
	s_addc_u32 s37, s37, 0
	s_mov_b32 m0, s61
	ds_read_b128 v[184:187], v177 offset:32768
	ds_read_b128 v[192:195], v177 offset:33792
	ds_read_b128 v[196:199], v177 offset:34816
	ds_read_b128 v[200:203], v177 offset:35840
	ds_read_b128 v[204:207], v177 offset:36864
	ds_read_b128 v[208:211], v177 offset:37888
	ds_read_b128 v[212:215], v177 offset:38912
	ds_read_b128 v[216:219], v177 offset:39936
	global_load_lds_dwordx4 v136, s[36:37]
	s_mov_b32 m0, s62
	s_nop 0
	global_load_lds_dwordx4 v140, s[36:37]
	s_waitcnt vmcnt(8)
	s_waitcnt lgkmcnt(0)
	s_barrier
	s_setprio 1
	s_waitcnt lgkmcnt(0)
	v_mfma_f32_16x16x32_bf16 v[124:127], v[128:131], v[184:187], v[124:127]
	v_mfma_f32_16x16x32_bf16 v[120:123], v[154:157], v[184:187], v[120:123]
	v_mfma_f32_16x16x32_bf16 v[116:119], v[128:131], v[196:199], v[116:119]
	v_mfma_f32_16x16x32_bf16 v[112:115], v[154:157], v[196:199], v[112:115]
	v_mfma_f32_16x16x32_bf16 v[108:111], v[128:131], v[204:207], v[108:111]
	v_mfma_f32_16x16x32_bf16 v[104:107], v[154:157], v[204:207], v[104:107]
	v_mfma_f32_16x16x32_bf16 v[100:103], v[128:131], v[212:215], v[100:103]
	v_mfma_f32_16x16x32_bf16 v[96:99], v[154:157], v[212:215], v[96:99]
	v_mfma_f32_16x16x32_bf16 v[124:127], v[132:135], v[192:195], v[124:127]
	v_mfma_f32_16x16x32_bf16 v[120:123], v[158:161], v[192:195], v[120:123]
	v_mfma_f32_16x16x32_bf16 v[116:119], v[132:135], v[200:203], v[116:119]
	v_mfma_f32_16x16x32_bf16 v[112:115], v[158:161], v[200:203], v[112:115]
	v_mfma_f32_16x16x32_bf16 v[108:111], v[132:135], v[208:211], v[108:111]
	v_mfma_f32_16x16x32_bf16 v[104:107], v[158:161], v[208:211], v[104:107]
	v_mfma_f32_16x16x32_bf16 v[100:103], v[132:135], v[216:219], v[100:103]
	v_mfma_f32_16x16x32_bf16 v[96:99], v[158:161], v[216:219], v[96:99]
	s_setprio 0
	s_setprio 1
	s_cbranch_vccnz .Lp1skip2
	v_mfma_f32_16x16x32_bf16 v[60:63], v[162:165], v[184:187], v[60:63]
	v_mfma_f32_16x16x32_bf16 v[56:59], v[170:173], v[184:187], v[56:59]
	v_mfma_f32_16x16x32_bf16 v[52:55], v[162:165], v[196:199], v[52:55]
	v_mfma_f32_16x16x32_bf16 v[48:51], v[170:173], v[196:199], v[48:51]
	v_mfma_f32_16x16x32_bf16 v[44:47], v[162:165], v[204:207], v[44:47]
	v_mfma_f32_16x16x32_bf16 v[40:43], v[170:173], v[204:207], v[40:43]
	v_mfma_f32_16x16x32_bf16 v[36:39], v[162:165], v[212:215], v[36:39]
	v_mfma_f32_16x16x32_bf16 v[32:35], v[170:173], v[212:215], v[32:35]
	v_mfma_f32_16x16x32_bf16 v[60:63], v[166:169], v[192:195], v[60:63]
	v_mfma_f32_16x16x32_bf16 v[56:59], v[180:183], v[192:195], v[56:59]
	v_mfma_f32_16x16x32_bf16 v[52:55], v[166:169], v[200:203], v[52:55]
	v_mfma_f32_16x16x32_bf16 v[48:51], v[180:183], v[200:203], v[48:51]
	v_mfma_f32_16x16x32_bf16 v[44:47], v[166:169], v[208:211], v[44:47]
	v_mfma_f32_16x16x32_bf16 v[40:43], v[180:183], v[208:211], v[40:43]
	v_mfma_f32_16x16x32_bf16 v[36:39], v[166:169], v[216:219], v[36:39]
	v_mfma_f32_16x16x32_bf16 v[32:35], v[180:183], v[216:219], v[32:35]
.Lp1skip2:
	s_setprio 0
	s_barrier
	s_add_i32 s36, s86, s56
	s_add_i32 m0, s36, 0xffffff80
	ds_read_b128 v[184:187], v177 offset:49152
	ds_read_b128 v[192:195], v177 offset:50176
	ds_read_b128 v[196:199], v177 offset:51200
	ds_read_b128 v[200:203], v177 offset:52224
	ds_read_b128 v[204:207], v177 offset:53248
	ds_read_b128 v[208:211], v177 offset:54272
	ds_read_b128 v[212:215], v177 offset:55296
	ds_read_b128 v[216:219], v177 offset:56320
	global_load_lds_dwordx4 v138, s[28:29] offset:128
	s_add_i32 m0, s36, 0x1f80
	s_add_i32 s36, s87, s56
	global_load_lds_dwordx4 v142, s[28:29] offset:128
	s_add_u32 s28, s28, 0x40080
	s_addc_u32 s29, s29, 0
	s_mov_b32 m0, s36
	s_nop 0
	global_load_lds_dwordx4 v138, s[28:29]
	s_add_i32 m0, s36, 0x2000
	s_nop 0
	global_load_lds_dwordx4 v142, s[28:29]
	s_add_i32 m0, s66, 0xffffff80
	s_nop 0
	global_load_lds_dwordx4 v136, s[98:99] offset:128
	s_add_i32 m0, s67, 0xffffff80
	s_nop 0
	global_load_lds_dwordx4 v140, s[98:99] offset:128
	s_waitcnt vmcnt(8)
	s_waitcnt lgkmcnt(0)
	s_barrier
	s_setprio 1
	s_waitcnt lgkmcnt(0)
	v_mfma_f32_16x16x32_bf16 v[92:95], v[128:131], v[184:187], v[92:95]
	v_mfma_f32_16x16x32_bf16 v[88:91], v[154:157], v[184:187], v[88:91]
	v_mfma_f32_16x16x32_bf16 v[84:87], v[128:131], v[196:199], v[84:87]
	v_mfma_f32_16x16x32_bf16 v[80:83], v[154:157], v[196:199], v[80:83]
	v_mfma_f32_16x16x32_bf16 v[76:79], v[128:131], v[204:207], v[76:79]
	v_mfma_f32_16x16x32_bf16 v[72:75], v[154:157], v[204:207], v[72:75]
	v_mfma_f32_16x16x32_bf16 v[68:71], v[128:131], v[212:215], v[68:71]
	v_mfma_f32_16x16x32_bf16 v[64:67], v[154:157], v[212:215], v[64:67]
	v_mfma_f32_16x16x32_bf16 v[92:95], v[132:135], v[192:195], v[92:95]
	v_mfma_f32_16x16x32_bf16 v[88:91], v[158:161], v[192:195], v[88:91]
	v_mfma_f32_16x16x32_bf16 v[84:87], v[132:135], v[200:203], v[84:87]
	v_mfma_f32_16x16x32_bf16 v[80:83], v[158:161], v[200:203], v[80:83]
	v_mfma_f32_16x16x32_bf16 v[76:79], v[132:135], v[208:211], v[76:79]
	v_mfma_f32_16x16x32_bf16 v[72:75], v[158:161], v[208:211], v[72:75]
	v_mfma_f32_16x16x32_bf16 v[68:71], v[132:135], v[216:219], v[68:71]
	v_mfma_f32_16x16x32_bf16 v[64:67], v[158:161], v[216:219], v[64:67]
	s_setprio 0
	s_setprio 1
	s_cbranch_vccnz .Lp1skip3
	v_mfma_f32_16x16x32_bf16 v[28:31], v[162:165], v[184:187], v[28:31]
	v_mfma_f32_16x16x32_bf16 v[24:27], v[170:173], v[184:187], v[24:27]
	v_mfma_f32_16x16x32_bf16 v[20:23], v[162:165], v[196:199], v[20:23]
	v_mfma_f32_16x16x32_bf16 v[16:19], v[170:173], v[196:199], v[16:19]
	v_mfma_f32_16x16x32_bf16 v[12:15], v[162:165], v[204:207], v[12:15]
	v_mfma_f32_16x16x32_bf16 v[8:11], v[170:173], v[204:207], v[8:11]
	v_mfma_f32_16x16x32_bf16 v[4:7], v[162:165], v[212:215], v[4:7]
	v_mfma_f32_16x16x32_bf16 v[0:3], v[170:173], v[212:215], v[0:3]
	v_mfma_f32_16x16x32_bf16 v[28:31], v[166:169], v[192:195], v[28:31]
	v_mfma_f32_16x16x32_bf16 v[24:27], v[180:183], v[192:195], v[24:27]
	v_mfma_f32_16x16x32_bf16 v[20:23], v[166:169], v[200:203], v[20:23]
	v_mfma_f32_16x16x32_bf16 v[16:19], v[180:183], v[200:203], v[16:19]
	v_mfma_f32_16x16x32_bf16 v[12:15], v[166:169], v[208:211], v[12:15]
	v_mfma_f32_16x16x32_bf16 v[8:11], v[180:183], v[208:211], v[8:11]
	v_mfma_f32_16x16x32_bf16 v[4:7], v[166:169], v[216:219], v[4:7]
	v_mfma_f32_16x16x32_bf16 v[0:3], v[180:183], v[216:219], v[0:3]
.Lp1skip3:
	s_setprio 0
	s_barrier
	s_add_u32 s10, s10, 0x100
	s_addc_u32 s11, s11, 0
	s_add_u32 s79, s79, 0x100
	s_addc_u32 s84, s84, 0
	s_cmp_ge_i32 s85, s3
	s_mov_b32 s28, s85
	s_cbranch_scc0 .LBB0_282
	s_and_b64 vcc, exec, s[44:45]
	s_cbranch_vccz .LBB0_285

.LBB0_571:
	s_or_b64 exec, exec, s[10:11]
	s_ashr_i32 s10, s47, 31
	s_waitcnt lgkmcnt(0)
	s_add_u32 s11, s47, s38
	v_mov_b64_e32 v[32:33], s[26:27]
	s_addc_u32 s10, s10, 0
	s_mov_b32 s47, s39
	v_mov_b32_e32 v169, v121
	ds_read_b128 v[34:37], v139 offset:41984
	ds_read_b128 v[38:41], v139 offset:42016
	ds_read_b128 v[42:45], v139 offset:42048
	ds_read_b128 v[46:49], v139 offset:42080
	s_lshr_b32 s98, s99, 10
	s_mulk_i32 s98, 0x1200
	v_bfe_u32 v67, v191, 5, 1
	v_mul_u32_u24_e32 v66, 0x48, v118
	v_lshl_add_u32 v66, v67, 3, v66
	v_add_u32_e32 v66, s98, v66
	v_bfe_u32 v68, v191, 2, 2
	v_lshl_add_u32 v68, v67, 5, v68
	v_mul_u32_u24_e32 v68, 0x48, v68
	v_bfe_u32 v69, v191, 4, 1
	v_lshlrev_b32_e32 v69, 2, v69
	v_and_b32_e32 v70, 3, v191
	v_add_u32_e32 v69, v69, v70
	v_lshl_add_u32 v68, v69, 3, v68
	v_add_u32_e32 v68, s98, v68
	v_or_b32_e32 v70, s11, v118
	v_mad_u64_u32 v[88:89], s[28:29], v70, s57, v[32:33]
	v_mad_i32_i24 v89, s10, v137, v89
	v_lshl_add_u64 v[88:89], v[88:89], 0, s[46:47]
	v_lshl_add_u64 v[88:89], v[88:89], 0, s[44:45]
	v_lshlrev_b32_e32 v90, 6, v67
	v_mov_b32_e32 v91, v121
	v_lshl_add_u64 v[88:89], v[88:89], 0, v[90:91]
	s_waitcnt lgkmcnt(0)
	v_pk_mul_f32 v[0:1], v[0:1], v[34:35]
	v_pk_mul_f32 v[16:17], v[16:17], v[34:35]
	v_pk_mul_f32 v[2:3], v[2:3], v[36:37]
	v_pk_mul_f32 v[18:19], v[18:19], v[36:37]
	v_pk_mul_f32 v[4:5], v[4:5], v[38:39]
	v_pk_mul_f32 v[20:21], v[20:21], v[38:39]
	v_pk_mul_f32 v[6:7], v[6:7], v[40:41]
	v_pk_mul_f32 v[22:23], v[22:23], v[40:41]
	v_pk_mul_f32 v[8:9], v[8:9], v[42:43]
	v_pk_mul_f32 v[24:25], v[24:25], v[42:43]
	v_pk_mul_f32 v[10:11], v[10:11], v[44:45]
	v_pk_mul_f32 v[26:27], v[26:27], v[44:45]
	v_pk_mul_f32 v[12:13], v[12:13], v[46:47]
	v_pk_mul_f32 v[28:29], v[28:29], v[46:47]
	v_pk_mul_f32 v[14:15], v[14:15], v[48:49]
	v_pk_mul_f32 v[30:31], v[30:31], v[48:49]
	v_cvt_pk_bf16_f32 v50, v0, v1
	v_cvt_pk_bf16_f32 v58, v16, v17
	v_cvt_pk_bf16_f32 v51, v2, v3
	v_cvt_pk_bf16_f32 v59, v18, v19
	v_cvt_pk_bf16_f32 v52, v4, v5
	v_cvt_pk_bf16_f32 v60, v20, v21
	v_cvt_pk_bf16_f32 v53, v6, v7
	v_cvt_pk_bf16_f32 v61, v22, v23
	v_cvt_pk_bf16_f32 v54, v8, v9
	v_cvt_pk_bf16_f32 v62, v24, v25
	v_cvt_pk_bf16_f32 v55, v10, v11
	v_cvt_pk_bf16_f32 v63, v26, v27
	v_cvt_pk_bf16_f32 v56, v12, v13
	v_cvt_pk_bf16_f32 v64, v28, v29
	v_cvt_pk_bf16_f32 v57, v14, v15
	v_cvt_pk_bf16_f32 v65, v30, v31
	ds_write_b64 v66, v[50:51] offset:0
	ds_write_b64 v66, v[58:59] offset:2304
	ds_write_b64 v66, v[52:53] offset:16
	ds_write_b64 v66, v[60:61] offset:2320
	ds_write_b64 v66, v[54:55] offset:32
	ds_write_b64 v66, v[62:63] offset:2336
	ds_write_b64 v66, v[56:57] offset:48
	ds_write_b64 v66, v[64:65] offset:2352
	s_waitcnt lgkmcnt(0)
	ds_read_b64_tr_b16 v[72:73], v68 offset:0
	ds_read_b64_tr_b16 v[74:75], v68 offset:288
	ds_read_b64_tr_b16 v[76:77], v68 offset:576
	ds_read_b64_tr_b16 v[78:79], v68 offset:864
	ds_read_b64_tr_b16 v[80:81], v68 offset:1152
	ds_read_b64_tr_b16 v[82:83], v68 offset:1440
	ds_read_b64_tr_b16 v[84:85], v68 offset:1728
	ds_read_b64_tr_b16 v[86:87], v68 offset:2016
	s_waitcnt lgkmcnt(0)
	global_store_dwordx4 v[88:89], v[72:75], off
	global_store_dwordx4 v[88:89], v[76:79], off offset:16
	global_store_dwordx4 v[88:89], v[80:83], off offset:32
	global_store_dwordx4 v[88:89], v[84:87], off offset:48
	s_add_i32 s61, s30, s61
	s_add_i32 s53, s53, s54
	s_add_i32 s60, s60, s30
	s_cmpk_lt_i32 s61, 0x200
	s_barrier
	s_cbranch_scc0 .LBB0_636

.LBB0_574:
	s_or_b64 exec, exec, s[10:11]
	v_lshl_add_u64 v[0:1], s[38:39], 0, v[122:123]
	s_lshl_b32 s10, s28, 6
	v_lshlrev_b64 v[0:1], 11, v[0:1]
	v_lshl_add_u64 v[0:1], s[8:9], 0, v[0:1]
	s_lshl_b32 s46, s10, 1
	s_mov_b32 s47, s39
	v_lshl_add_u64 v[0:1], v[0:1], 0, s[46:47]
	v_mov_b32_e32 v167, v121
	v_lshl_add_u64 v[180:181], v[0:1], 0, v[166:167]
	v_and_b32_e32 v237, 16, v191
	v_lshlrev_b32_e32 v237, 2, v237
	v_xor_b32_e32 v234, v237, v180
	v_mov_b32_e32 v235, v181
	global_load_dwordx4 v[112:115], v[234:235], off offset:1024
	s_waitcnt vmcnt(0)
	ds_write_b128 v119, v[104:107]
	ds_write_b128 v119, v[104:107] offset:45056
	s_and_saveexec_b64 s[10:11], s[4:5]
	ds_write_b128 v119, v[108:111] offset:8192
	ds_write_b128 v119, v[108:111] offset:53248
	s_or_b64 exec, exec, s[10:11]
	s_lshl_b32 s10, s53, 11
	s_and_b32 s11, s60, 7
	s_and_b32 s10, s10, 0x3800000
	s_lshl_b32 s11, s11, 7
	s_or_b32 s10, s10, s11
	s_mov_b32 s11, s39
	v_lshl_add_u64 v[170:171], v[160:161], 0, s[10:11]
	s_lshl_b32 s28, s53, 6
	v_lshl_add_u64 v[174:175], v[164:165], 0, s[10:11]
	s_add_i32 s10, s62, 0x100
	s_and_b32 s28, s28, 0x1c0000
	s_mov_b32 s29, s39
	s_ashr_i32 s47, s10, 6
	v_lshl_add_u64 v[172:173], v[162:163], 0, s[28:29]
	s_cmp_lt_i32 s47, 1
	ds_write_b128 v119, v[112:115] offset:24576
	ds_write_b128 v119, v[112:115] offset:57344
	s_waitcnt lgkmcnt(0)
	s_barrier
	s_cbranch_scc1 .LBB0_601
	v_mov_b32_e32 v14, v121
	v_mov_b32_e32 v15, v121
	v_mov_b32_e32 v0, v121
	v_mov_b32_e32 v1, v121
	v_mov_b32_e32 v2, v121
	v_mov_b32_e32 v3, v121
	v_mov_b32_e32 v4, v121
	v_mov_b32_e32 v5, v121
	v_mov_b32_e32 v6, v121
	v_mov_b32_e32 v7, v121
	v_mov_b32_e32 v8, v121
	v_mov_b32_e32 v9, v121
	v_mov_b32_e32 v10, v121
	v_mov_b32_e32 v11, v121
	v_mov_b32_e32 v12, v121
	v_mov_b32_e32 v13, v121
	v_mov_b32_e32 v141, 0
	v_mov_b64_e32 v[30:31], v[14:15]
	s_or_b32 s49, s63, 31
	s_sub_i32 s64, 0, s47
	s_mov_b32 s65, 1
	s_mov_b32 s66, 63
	v_mov_b64_e32 v[184:185], v[174:175]
	v_mov_b64_e32 v[186:187], v[172:173]
	v_mov_b64_e32 v[188:189], v[170:171]
	v_xor_b32_e32 v188, v237, v188
	v_bfe_u32 v232, v191, 2, 2
	v_bfe_u32 v233, v191, 5, 1
	v_lshl_add_u32 v233, v233, 2, v232
	v_lshlrev_b32_e32 v238, 7, v233
	v_bfe_u32 v233, v191, 4, 1
	v_bfe_u32 v234, v191, 1, 1
	v_lshl_or_b32 v233, v233, 1, v234
	v_lshrrev_b32_e32 v232, 1, v232
	v_lshlrev_b32_e32 v232, 2, v232
	v_xor_b32_e32 v233, v233, v232
	v_lshl_add_u32 v238, v233, 4, v238
	v_and_b32_e32 v232, 1, v191
	v_lshl_add_u32 v238, v232, 3, v238
	v_xor_b32_e32 v239, 64, v238
	v_readfirstlane_b32 s99, v119
	s_sub_i32 s98, s3, s62
	s_addk_i32 s98, 0xf00
	v_or_b32_e32 v232, s98, v118
	v_ashrrev_i32_e32 v233, 31, v232
	v_lshl_add_u64 v[232:233], v[232:233], 0, s[38:39]
	v_mov_b64_e32 v[234:235], s[0:1]
	v_mad_u64_u32 v[234:235], s[10:11], v232, s55, v[234:235]
	v_mad_i32_i24 v235, v233, s55, v235
	s_mov_b32 s100, s48
	s_mov_b32 s101, 0
	v_lshl_add_u64 v[232:233], v[234:235], 0, s[100:101]
	v_lshl_add_u64 v[232:233], v[232:233], 0, v[120:121]
	s_mul_i32 s98, s99, 6
	s_add_i32 s98, s98, 0x10000
	s_mov_b32 m0, s98
	s_nop 0
	global_load_lds_dwordx4 v[232:233], off
	s_add_i32 m0, s98, 0x3e0
	s_nop 0
	global_load_lds_dwordx4 v[232:233], off offset:32
	s_add_i32 m0, s98, 0x7c0
	s_nop 0
	global_load_lds_dwordx4 v[232:233], off offset:64
	s_add_i32 m0, s98, 0xba0
	s_nop 0
	global_load_lds_dwordx4 v[232:233], off offset:96
	s_add_i32 m0, s98, 0xf80
	s_nop 0
	global_load_lds_dwordx4 v[232:233], off offset:128
	s_add_i32 m0, s98, 0x1360
	s_nop 0
	global_load_lds_dwordx4 v[232:233], off offset:160
	v_mov_b64_e32 v[28:29], v[12:13]
	v_mov_b64_e32 v[26:27], v[10:11]
	v_mov_b64_e32 v[24:25], v[8:9]
	v_mov_b64_e32 v[22:23], v[6:7]
	v_mov_b64_e32 v[20:21], v[4:5]
	v_mov_b64_e32 v[18:19], v[2:3]
	v_mov_b64_e32 v[16:17], v[0:1]
	v_mov_b32_e32 v139, 0
	v_mov_b32_e32 v32, 0
	v_mov_b32_e32 v33, v141
	v_mov_b32_e32 v34, v141
	v_mov_b32_e32 v35, v141
	v_mov_b32_e32 v36, v141
	v_mov_b32_e32 v37, v141
	v_mov_b32_e32 v38, v141
	v_mov_b32_e32 v39, v141
	v_mov_b32_e32 v40, v141
	v_mov_b32_e32 v41, v141
	v_mov_b32_e32 v42, v141
	v_mov_b32_e32 v43, v141
	v_mov_b32_e32 v44, v141
	v_mov_b32_e32 v45, v141
	v_mov_b32_e32 v46, v141
	v_mov_b32_e32 v47, v141
	s_branch .LBB0_580

.LBB0_604:
	s_or_b64 exec, exec, s[10:11]
	s_ashr_i32 s10, s63, 31
	s_waitcnt lgkmcnt(0)
	s_add_u32 s11, s63, s38
	v_add_u32_e32 v139, s52, v117
	v_mov_b64_e32 v[32:33], s[26:27]
	s_addc_u32 s10, s10, 0
	s_mov_b32 s47, s39
	v_mov_b32_e32 v169, v121
	ds_read_b128 v[34:37], v139 offset:41984
	ds_read_b128 v[38:41], v139 offset:42016
	ds_read_b128 v[42:45], v139 offset:42048
	ds_read_b128 v[46:49], v139 offset:42080
	s_lshr_b32 s98, s99, 10
	s_mulk_i32 s98, 0x1200
	v_bfe_u32 v67, v191, 5, 1
	v_mul_u32_u24_e32 v66, 0x48, v118
	v_lshl_add_u32 v66, v67, 3, v66
	v_add_u32_e32 v66, s98, v66
	v_bfe_u32 v68, v191, 2, 2
	v_lshl_add_u32 v68, v67, 5, v68
	v_mul_u32_u24_e32 v68, 0x48, v68
	v_bfe_u32 v69, v191, 4, 1
	v_lshlrev_b32_e32 v69, 2, v69
	v_and_b32_e32 v70, 3, v191
	v_add_u32_e32 v69, v69, v70
	v_lshl_add_u32 v68, v69, 3, v68
	v_add_u32_e32 v68, s98, v68
	v_or_b32_e32 v70, s11, v118
	v_mad_u64_u32 v[88:89], s[28:29], v70, s57, v[32:33]
	v_mad_i32_i24 v89, s10, v137, v89
	v_lshl_add_u64 v[88:89], v[88:89], 0, s[46:47]
	v_lshl_add_u64 v[88:89], v[88:89], 0, s[44:45]
	v_lshlrev_b32_e32 v90, 6, v67
	v_mov_b32_e32 v91, v121
	v_lshl_add_u64 v[88:89], v[88:89], 0, v[90:91]
	s_waitcnt lgkmcnt(0)
	v_pk_mul_f32 v[0:1], v[0:1], v[34:35]
	v_pk_mul_f32 v[16:17], v[16:17], v[34:35]
	v_pk_mul_f32 v[2:3], v[2:3], v[36:37]
	v_pk_mul_f32 v[18:19], v[18:19], v[36:37]
	v_pk_mul_f32 v[4:5], v[4:5], v[38:39]
	v_pk_mul_f32 v[20:21], v[20:21], v[38:39]
	v_pk_mul_f32 v[6:7], v[6:7], v[40:41]
	v_pk_mul_f32 v[22:23], v[22:23], v[40:41]
	v_pk_mul_f32 v[8:9], v[8:9], v[42:43]
	v_pk_mul_f32 v[24:25], v[24:25], v[42:43]
	v_pk_mul_f32 v[10:11], v[10:11], v[44:45]
	v_pk_mul_f32 v[26:27], v[26:27], v[44:45]
	v_pk_mul_f32 v[12:13], v[12:13], v[46:47]
	v_pk_mul_f32 v[28:29], v[28:29], v[46:47]
	v_pk_mul_f32 v[14:15], v[14:15], v[48:49]
	v_pk_mul_f32 v[30:31], v[30:31], v[48:49]
	v_cvt_pk_bf16_f32 v50, v0, v1
	v_cvt_pk_bf16_f32 v58, v16, v17
	v_cvt_pk_bf16_f32 v51, v2, v3
	v_cvt_pk_bf16_f32 v59, v18, v19
	v_cvt_pk_bf16_f32 v52, v4, v5
	v_cvt_pk_bf16_f32 v60, v20, v21
	v_cvt_pk_bf16_f32 v53, v6, v7
	v_cvt_pk_bf16_f32 v61, v22, v23
	v_cvt_pk_bf16_f32 v54, v8, v9
	v_cvt_pk_bf16_f32 v62, v24, v25
	v_cvt_pk_bf16_f32 v55, v10, v11
	v_cvt_pk_bf16_f32 v63, v26, v27
	v_cvt_pk_bf16_f32 v56, v12, v13
	v_cvt_pk_bf16_f32 v64, v28, v29
	v_cvt_pk_bf16_f32 v57, v14, v15
	v_cvt_pk_bf16_f32 v65, v30, v31
	ds_write_b64 v66, v[50:51] offset:0
	ds_write_b64 v66, v[58:59] offset:2304
	ds_write_b64 v66, v[52:53] offset:16
	ds_write_b64 v66, v[60:61] offset:2320
	ds_write_b64 v66, v[54:55] offset:32
	ds_write_b64 v66, v[62:63] offset:2336
	ds_write_b64 v66, v[56:57] offset:48
	ds_write_b64 v66, v[64:65] offset:2352
	s_waitcnt lgkmcnt(0)
	ds_read_b64_tr_b16 v[72:73], v68 offset:0
	ds_read_b64_tr_b16 v[74:75], v68 offset:288
	ds_read_b64_tr_b16 v[76:77], v68 offset:576
	ds_read_b64_tr_b16 v[78:79], v68 offset:864
	ds_read_b64_tr_b16 v[80:81], v68 offset:1152
	ds_read_b64_tr_b16 v[82:83], v68 offset:1440
	ds_read_b64_tr_b16 v[84:85], v68 offset:1728
	ds_read_b64_tr_b16 v[86:87], v68 offset:2016
	s_waitcnt lgkmcnt(0)
	global_store_dwordx4 v[88:89], v[72:75], off
	global_store_dwordx4 v[88:89], v[76:79], off offset:16
	global_store_dwordx4 v[88:89], v[80:83], off offset:32
	global_store_dwordx4 v[88:89], v[84:87], off offset:48
	s_sub_i32 s47, s3, s62
	s_addk_i32 s47, 0xf00
	v_or_b32_e32 v182, s47, v118
	v_ashrrev_i32_e32 v183, 31, v182
	v_lshl_add_u64 v[0:1], v[182:183], 0, s[38:39]
	v_mov_b64_e32 v[2:3], s[0:1]
	v_mad_u64_u32 v[2:3], s[10:11], v0, s55, v[2:3]
	v_mad_i32_i24 v3, v1, s55, v3
	s_mov_b32 s49, s39
	v_lshl_add_u64 v[0:1], v[2:3], 0, s[48:49]
	v_lshl_add_u64 v[0:1], v[0:1], 0, v[120:121]
	s_barrier
	s_mul_i32 s98, s99, 5
	s_add_i32 s98, s98, 0x10000
	v_add_u32_e32 v232, s98, v119
	s_waitcnt vmcnt(0)
	ds_read_b128 v[100:103], v232
	ds_read_b128 v[80:83], v232 offset:1024
	ds_read_b128 v[84:87], v232 offset:2048
	ds_read_b128 v[88:91], v232 offset:3072
	ds_read_b128 v[92:95], v232 offset:4096
	ds_read_b128 v[96:99], v232 offset:5120
	v_and_b32_e32 v237, 16, v191
	v_lshlrev_b32_e32 v237, 2, v237
	s_sub_i32 s10, 0x1000, s62
	s_ashr_i32 s50, s10, 6
	s_cmp_lt_i32 s50, 1
	s_waitcnt lgkmcnt(0)
	s_barrier
	s_cbranch_scc1 .LBB0_633
	v_mov_b32_e32 v14, v121
	v_mov_b32_e32 v15, v121
	v_mov_b32_e32 v0, v121
	v_mov_b32_e32 v1, v121
	v_mov_b32_e32 v2, v121
	v_mov_b32_e32 v3, v121
	v_mov_b32_e32 v4, v121
	v_mov_b32_e32 v5, v121
	v_mov_b32_e32 v6, v121
	v_mov_b32_e32 v7, v121
	v_mov_b32_e32 v8, v121
	v_mov_b32_e32 v9, v121
	v_mov_b32_e32 v10, v121
	v_mov_b32_e32 v11, v121
	v_mov_b32_e32 v12, v121
	v_mov_b32_e32 v13, v121
	v_mov_b32_e32 v143, 0
	v_mov_b64_e32 v[30:31], v[14:15]
	s_or_b32 s51, s47, 31
	s_sub_i32 s62, 0, s50
	s_mov_b32 s63, 1
	s_mov_b32 s64, 63
	v_mov_b64_e32 v[28:29], v[12:13]
	v_mov_b64_e32 v[26:27], v[10:11]
	v_mov_b64_e32 v[24:25], v[8:9]
	v_mov_b64_e32 v[22:23], v[6:7]
	v_mov_b64_e32 v[20:21], v[4:5]
	v_mov_b64_e32 v[18:19], v[2:3]
	v_mov_b64_e32 v[16:17], v[0:1]
	v_mov_b32_e32 v141, 0
	v_mov_b32_e32 v32, 0
	v_mov_b32_e32 v33, v143
	v_mov_b32_e32 v34, v143
	v_mov_b32_e32 v35, v143
	v_mov_b32_e32 v36, v143
	v_mov_b32_e32 v37, v143
	v_mov_b32_e32 v38, v143
	v_mov_b32_e32 v39, v143
	v_mov_b32_e32 v40, v143
	v_mov_b32_e32 v41, v143
	v_mov_b32_e32 v42, v143
	v_mov_b32_e32 v43, v143
	v_mov_b32_e32 v44, v143
	v_mov_b32_e32 v45, v143
	v_mov_b32_e32 v46, v143
	v_mov_b32_e32 v47, v143
	v_bfe_u32 v232, v191, 2, 2
	v_bfe_u32 v233, v191, 5, 1
	v_lshl_add_u32 v233, v233, 2, v232
	v_lshlrev_b32_e32 v238, 7, v233
	v_bfe_u32 v233, v191, 4, 1
	v_bfe_u32 v234, v191, 1, 1
	v_lshl_or_b32 v233, v233, 1, v234
	v_lshrrev_b32_e32 v232, 1, v232
	v_lshlrev_b32_e32 v232, 2, v232
	v_xor_b32_e32 v233, v233, v232
	v_lshl_add_u32 v238, v233, 4, v238
	v_and_b32_e32 v232, 1, v191
	v_lshl_add_u32 v238, v232, 3, v238
	v_xor_b32_e32 v239, 64, v238
	v_readfirstlane_b32 s99, v119
	v_xor_b32_e32 v170, v237, v170
	s_branch .LBB0_612

.LBB0_616:
	s_add_i32 s10, s63, -1
	s_and_b32 s65, s10, 1
	s_sub_i32 s10, s64, 63
	s_cmp_gt_i32 s10, s51
	s_cbranch_scc1 .LBB0_629
	s_mul_i32 s10, s65, 0x3000
	s_cmp_eq_u32 s63, 1
	s_cselect_b32 s10, 0xb000, s10
	v_add_u32_e32 v52, s10, v129
	ds_read_b128 v[48:51], v52
	ds_read_b128 v[176:179], v52 offset:512
	ds_read_b128 v[184:187], v52 offset:2048
	ds_read_b128 v[192:195], v52 offset:2560
	ds_read_b128 v[196:199], v52 offset:4096
	ds_read_b128 v[200:203], v52 offset:4608
	ds_read_b128 v[204:207], v52 offset:6144
	ds_read_b128 v[208:211], v52 offset:6656
	ds_read_b128 v[212:215], v52 offset:8192
	ds_read_b128 v[216:219], v52 offset:8704
	ds_read_b128 v[220:223], v52 offset:10240
	ds_read_b128 v[224:227], v52 offset:10752
	s_setprio 1
	s_waitcnt lgkmcnt(11)
	v_mfma_f32_32x32x16_bf16 v[64:79], v[48:51], v[100:103], v[32:47]
	s_waitcnt lgkmcnt(9)
	v_mfma_f32_32x32x16_bf16 v[64:79], v[184:187], v[80:83], v[64:79]
	v_mfma_f32_32x32x16_bf16 v[48:63], v[176:179], v[100:103], v[32:47]
	s_waitcnt lgkmcnt(8)
	v_mfma_f32_32x32x16_bf16 v[48:63], v[192:195], v[80:83], v[48:63]
	s_waitcnt lgkmcnt(7)
	v_mfma_f32_32x32x16_bf16 v[64:79], v[196:199], v[84:87], v[64:79]
	s_waitcnt lgkmcnt(6)
	v_mfma_f32_32x32x16_bf16 v[48:63], v[200:203], v[84:87], v[48:63]
	s_waitcnt lgkmcnt(5)
	v_mfma_f32_32x32x16_bf16 v[64:79], v[204:207], v[88:91], v[64:79]
	s_waitcnt lgkmcnt(4)
	v_mfma_f32_32x32x16_bf16 v[48:63], v[208:211], v[88:91], v[48:63]
	s_waitcnt lgkmcnt(3)
	v_mfma_f32_32x32x16_bf16 v[64:79], v[212:215], v[92:95], v[64:79]
	s_waitcnt lgkmcnt(2)
	v_mfma_f32_32x32x16_bf16 v[48:63], v[216:219], v[92:95], v[48:63]
	s_waitcnt lgkmcnt(1)
	v_mfma_f32_32x32x16_bf16 v[64:79], v[220:223], v[96:99], v[64:79]
	s_waitcnt lgkmcnt(0)
	v_mfma_f32_32x32x16_bf16 v[48:63], v[224:227], v[96:99], v[48:63]
	s_setprio 0
	s_cmp_le_i32 s64, s47
	s_cbranch_scc1 .LBB0_619
	v_add_u32_e32 v145, s64, v126
	v_subrev_u32_e32 v149, 31, v145
	v_subrev_u32_e32 v147, 63, v145
	v_cmp_le_i32_e32 vcc, v149, v182
	s_nop 4
	v_cndmask_b32_e32 v48, v135, v48, vcc
	v_cmp_lt_i32_e32 vcc, v147, v182
	s_nop 1
	v_cndmask_b32_e32 v65, v135, v65, vcc
	v_cmp_le_i32_e32 vcc, v147, v182
	v_subrev_u32_e32 v147, 30, v145
	s_nop 0
	v_cndmask_b32_e32 v64, v135, v64, vcc
	v_cmp_le_i32_e32 vcc, v147, v182
	v_subrev_u32_e32 v147, 61, v145
	s_nop 0
	v_cndmask_b32_e32 v49, v135, v49, vcc
	v_cmp_le_i32_e32 vcc, v147, v182
	v_subrev_u32_e32 v147, 29, v145
	s_nop 0
	v_cndmask_b32_e32 v66, v135, v66, vcc
	v_cmp_le_i32_e32 vcc, v147, v182
	v_subrev_u32_e32 v147, 60, v145
	s_nop 0
	v_cndmask_b32_e32 v50, v135, v50, vcc
	v_cmp_le_i32_e32 vcc, v147, v182
	v_subrev_u32_e32 v147, 28, v145
	s_nop 0
	v_cndmask_b32_e32 v67, v135, v67, vcc
	v_cmp_le_i32_e32 vcc, v147, v182
	v_subrev_u32_e32 v147, 55, v145
	s_nop 0
	v_cndmask_b32_e32 v51, v135, v51, vcc
	v_cmp_le_i32_e32 vcc, v147, v182
	v_subrev_u32_e32 v147, 23, v145
	s_nop 0
	v_cndmask_b32_e32 v68, v135, v68, vcc
	v_cmp_le_i32_e32 vcc, v147, v182
	v_subrev_u32_e32 v147, 54, v145
	s_nop 0
	v_cndmask_b32_e32 v52, v135, v52, vcc
	v_cmp_le_i32_e32 vcc, v147, v182
	v_subrev_u32_e32 v147, 22, v145
	s_nop 0
	v_cndmask_b32_e32 v69, v135, v69, vcc
	v_cmp_le_i32_e32 vcc, v147, v182
	v_subrev_u32_e32 v147, 53, v145
	s_nop 0
	v_cndmask_b32_e32 v53, v135, v53, vcc
	v_cmp_le_i32_e32 vcc, v147, v182
	v_subrev_u32_e32 v147, 21, v145
	s_nop 0
	v_cndmask_b32_e32 v70, v135, v70, vcc
	v_cmp_le_i32_e32 vcc, v147, v182
	v_subrev_u32_e32 v147, 52, v145
	s_nop 0
	v_cndmask_b32_e32 v54, v135, v54, vcc
	v_cmp_le_i32_e32 vcc, v147, v182
	v_subrev_u32_e32 v147, 20, v145
	s_nop 0
	v_cndmask_b32_e32 v71, v135, v71, vcc
	v_cmp_le_i32_e32 vcc, v147, v182
	v_subrev_u32_e32 v147, 47, v145
	s_nop 0
	v_cndmask_b32_e32 v55, v135, v55, vcc
	v_cmp_le_i32_e32 vcc, v147, v182
	v_add_u32_e32 v147, -15, v145
	s_nop 0
	v_cndmask_b32_e32 v72, v135, v72, vcc
	v_cmp_le_i32_e32 vcc, v147, v182
	v_subrev_u32_e32 v147, 46, v145
	s_nop 0
	v_cndmask_b32_e32 v56, v135, v56, vcc
	v_cmp_le_i32_e32 vcc, v147, v182
	v_add_u32_e32 v147, -14, v145
	s_nop 0
	v_cndmask_b32_e32 v73, v135, v73, vcc
	v_cmp_le_i32_e32 vcc, v147, v182
	v_subrev_u32_e32 v147, 45, v145
	s_nop 0
	v_cndmask_b32_e32 v57, v135, v57, vcc
	v_cmp_le_i32_e32 vcc, v147, v182
	v_add_u32_e32 v147, -13, v145
	s_nop 0
	v_cndmask_b32_e32 v74, v135, v74, vcc
	v_cmp_le_i32_e32 vcc, v147, v182
	v_subrev_u32_e32 v147, 44, v145
	s_nop 0
	v_cndmask_b32_e32 v58, v135, v58, vcc
	v_cmp_le_i32_e32 vcc, v147, v182
	v_add_u32_e32 v147, -12, v145
	s_nop 0
	v_cndmask_b32_e32 v75, v135, v75, vcc
	v_cmp_le_i32_e32 vcc, v147, v182
	v_subrev_u32_e32 v147, 39, v145
	s_nop 0
	v_cndmask_b32_e32 v59, v135, v59, vcc
	v_cmp_le_i32_e32 vcc, v147, v182
	v_add_u32_e32 v147, -7, v145
	s_nop 0
	v_cndmask_b32_e32 v76, v135, v76, vcc
	v_cmp_le_i32_e32 vcc, v147, v182
	v_subrev_u32_e32 v147, 38, v145
	s_nop 0
	v_cndmask_b32_e32 v60, v135, v60, vcc
	v_cmp_le_i32_e32 vcc, v147, v182
	v_add_u32_e32 v147, -6, v145
	s_nop 0
	v_cndmask_b32_e32 v77, v135, v77, vcc
	v_cmp_le_i32_e32 vcc, v147, v182
	v_subrev_u32_e32 v147, 37, v145
	s_nop 0
	v_cndmask_b32_e32 v61, v135, v61, vcc
	v_cmp_le_i32_e32 vcc, v147, v182
	v_add_u32_e32 v147, -5, v145
	s_nop 0
	v_cndmask_b32_e32 v78, v135, v78, vcc
	v_cmp_le_i32_e32 vcc, v147, v182
	v_subrev_u32_e32 v147, 36, v145
	v_add_u32_e32 v145, -4, v145
	v_cndmask_b32_e32 v62, v135, v62, vcc
	v_cmp_le_i32_e32 vcc, v147, v182
	s_nop 1
	v_cndmask_b32_e32 v79, v135, v79, vcc
	v_cmp_le_i32_e32 vcc, v145, v182
	s_nop 1
	v_cndmask_b32_e32 v63, v135, v63, vcc

.LBB0_628:
	s_mul_i32 s10, s65, 0x2200
	s_cmp_eq_u32 s63, 1
	s_cselect_b32 s10, 0x8000, s10
	v_add_u32_e32 v232, s10, v238
	v_add_u32_e32 v233, s10, v239
	ds_read_b64_tr_b16 v[212:213], v232 offset:24576
	ds_read_b64_tr_b16 v[214:215], v232 offset:25600
	ds_read_b64_tr_b16 v[216:217], v232 offset:26624
	ds_read_b64_tr_b16 v[218:219], v232 offset:27648
	ds_read_b64_tr_b16 v[220:221], v233 offset:24576
	ds_read_b64_tr_b16 v[222:223], v233 offset:25600
	ds_read_b64_tr_b16 v[224:225], v233 offset:26624
	ds_read_b64_tr_b16 v[226:227], v233 offset:27648
	ds_read_b64_tr_b16 v[228:229], v232 offset:28672
	ds_read_b64_tr_b16 v[230:231], v232 offset:29696
	v_exp_f32_e32 v176, v64
	v_exp_f32_e32 v177, v65
	v_exp_f32_e32 v180, v48
	v_exp_f32_e32 v181, v49
	v_exp_f32_e32 v178, v66
	v_exp_f32_e32 v179, v67
	v_exp_f32_e32 v186, v50
	v_exp_f32_e32 v187, v51
	v_exp_f32_e32 v184, v68
	v_exp_f32_e32 v185, v69
	v_pk_add_f32 v[48:49], v[180:181], v[176:177]
	v_exp_f32_e32 v188, v52
	v_exp_f32_e32 v189, v53
	v_pk_add_f32 v[48:49], v[178:179], v[48:49]
	v_exp_f32_e32 v192, v70
	v_exp_f32_e32 v193, v71
	v_pk_add_f32 v[48:49], v[186:187], v[48:49]
	v_exp_f32_e32 v194, v54
	v_exp_f32_e32 v195, v55
	v_pk_add_f32 v[48:49], v[184:185], v[48:49]
	v_exp_f32_e32 v196, v72
	v_exp_f32_e32 v197, v73
	v_pk_add_f32 v[48:49], v[188:189], v[48:49]
	v_exp_f32_e32 v198, v56
	v_exp_f32_e32 v199, v57
	v_pk_add_f32 v[48:49], v[192:193], v[48:49]
	v_exp_f32_e32 v200, v74
	v_exp_f32_e32 v201, v75
	v_pk_add_f32 v[48:49], v[194:195], v[48:49]
	v_exp_f32_e32 v202, v58
	v_exp_f32_e32 v203, v59
	v_pk_add_f32 v[48:49], v[196:197], v[48:49]
	v_exp_f32_e32 v204, v76
	v_exp_f32_e32 v205, v77
	v_pk_add_f32 v[48:49], v[198:199], v[48:49]
	v_exp_f32_e32 v206, v60
	v_exp_f32_e32 v207, v61
	v_pk_add_f32 v[48:49], v[200:201], v[48:49]
	v_exp_f32_e32 v208, v78
	v_exp_f32_e32 v209, v79
	v_pk_add_f32 v[48:49], v[202:203], v[48:49]
	v_exp_f32_e32 v210, v62
	v_exp_f32_e32 v211, v63
	v_pk_add_f32 v[48:49], v[204:205], v[48:49]
	v_pk_add_f32 v[48:49], v[206:207], v[48:49]
	v_pk_add_f32 v[48:49], v[208:209], v[48:49]
	v_pk_add_f32 v[48:49], v[210:211], v[48:49]
	v_pk_add_f32 v[48:49], v[48:49], v[48:49] op_sel:[0,1] op_sel_hi:[1,0]
	v_cvt_pk_bf16_f32 v176, v176, v177
	v_mov_b32_e32 v49, v48
	s_nop 1
	v_permlane32_swap_b32_e32 v48, v49
	v_add_f32_e32 v145, v48, v49
	ds_read_b64_tr_b16 v[68:69], v233 offset:28672
	ds_read_b64_tr_b16 v[70:71], v233 offset:29696
	ds_read_b64_tr_b16 v[72:73], v232 offset:30720
	ds_read_b64_tr_b16 v[74:75], v232 offset:31744
	ds_read_b64_tr_b16 v[76:77], v233 offset:30720
	ds_read_b64_tr_b16 v[78:79], v233 offset:31744
	v_cvt_pk_bf16_f32 v177, v178, v179
	v_cvt_pk_bf16_f32 v178, v184, v185
	v_cvt_pk_bf16_f32 v179, v192, v193
	v_cvt_pk_bf16_f32 v184, v180, v181
	v_cvt_pk_bf16_f32 v185, v186, v187
	v_cvt_pk_bf16_f32 v186, v188, v189
	v_cvt_pk_bf16_f32 v187, v194, v195
	v_cvt_pk_bf16_f32 v192, v196, v197
	v_cvt_pk_bf16_f32 v193, v200, v201
	v_cvt_pk_bf16_f32 v194, v204, v205
	v_cvt_pk_bf16_f32 v195, v208, v209
	v_cvt_pk_bf16_f32 v196, v198, v199
	v_cvt_pk_bf16_f32 v197, v202, v203
	v_cvt_pk_bf16_f32 v198, v206, v207
	v_cvt_pk_bf16_f32 v199, v210, v211
	s_setprio 1
	s_waitcnt lgkmcnt(14)
	v_mfma_f32_32x32x16_bf16 v[0:15], v[176:179], v[212:215], v[0:15]
	v_add_f32_e32 v141, v141, v145
	s_waitcnt lgkmcnt(10)
	v_mfma_f32_32x32x16_bf16 v[16:31], v[176:179], v[220:223], v[16:31]
	v_mfma_f32_32x32x16_bf16 v[0:15], v[192:195], v[216:219], v[0:15]
	s_waitcnt lgkmcnt(8)
	v_mfma_f32_32x32x16_bf16 v[16:31], v[192:195], v[224:227], v[16:31]
	s_waitcnt lgkmcnt(6)
	v_mfma_f32_32x32x16_bf16 v[0:15], v[184:187], v[228:231], v[0:15]
	s_waitcnt lgkmcnt(4)
	v_mfma_f32_32x32x16_bf16 v[16:31], v[184:187], v[68:71], v[16:31]
	s_waitcnt lgkmcnt(2)
	v_mfma_f32_32x32x16_bf16 v[0:15], v[196:199], v[72:75], v[0:15]
	s_waitcnt lgkmcnt(0)
	v_mfma_f32_32x32x16_bf16 v[16:31], v[196:199], v[76:79], v[16:31]
	s_setprio 0

.LBB0_713:
	v_readlane_b32 s84, v236, 43
	v_readlane_b32 s85, v236, 44
	v_and_b32_e32 v157, 15, v191
	v_lshrrev_b32_e32 v156, 2, v191
	v_and_or_b32 v157, v156, 64, v157
	v_lshrrev_b32_e32 v156, 1, v191
	v_and_b32_e32 v156, 0x78, v156
	v_lshlrev_b32_e32 v156, 1, v156
	v_lshrrev_b32_e32 v158, 1, v156
	v_lshrrev_b32_e32 v154, 4, v158
	v_lshlrev_b32_e32 v154, 20, v154
	v_lshl_add_u32 v154, v157, 5, v154
	v_and_b32_e32 v159, 15, v158
	v_lshl_add_u32 v154, v159, 1, v154
	v_lshl_add_u32 v155, v157, 10, v156
	v_lshlrev_b32_e32 v157, 1, v156
	v_mov_b32_e32 v160, 0xbfb8aa3b
	v_mov_b32_e32 v161, 0xbfb8aa3b
	s_lshl_b32 s10, s53, 24
	s_lshl_b32 s11, s52, 13
	s_add_i32 s10, s10, s11
	s_add_u32 s98, s0, s10
	s_addc_u32 s99, s1, 0
	s_lshl_b32 s10, s52, 18
	s_lshl_b32 s11, s53, 9
	s_add_i32 s10, s10, s11
	s_add_u32 s100, s20, s10
	s_addc_u32 s101, s21, 0
	s_lshl_b32 s10, s53, 10
	s_add_u32 s10, s84, s10
	s_addc_u32 s11, s85, 0
	global_load_dwordx4 v[128:131], v157, s[10:11]
	global_load_dwordx4 v[132:135], v157, s[10:11] offset:16
	v_mov_b32_e32 v156, v154
	global_load_dwordx4 v[170:173], v156, s[98:99]
	v_add_u32_e32 v156, 0x200, v154
	global_load_dwordx4 v[174:177], v156, s[98:99]
	v_add_u32_e32 v156, 0x400, v154
	global_load_dwordx4 v[178:181], v156, s[98:99]
	v_add_u32_e32 v156, 0x600, v154
	global_load_dwordx4 v[182:185], v156, s[98:99]
	v_add_u32_e32 v156, 0x1000, v154
	global_load_dwordx4 v[186:189], v156, s[98:99]
	v_add_u32_e32 v156, 0x1200, v154
	global_load_dwordx4 v[192:195], v156, s[98:99]
	v_add_u32_e32 v156, 0x1400, v154
	global_load_dwordx4 v[196:199], v156, s[98:99]
	v_add_u32_e32 v156, 0x1600, v154
	global_load_dwordx4 v[200:203], v156, s[98:99]
	v_add_u32_e32 v156, 0x800000, v154
	global_load_dwordx4 v[204:207], v156, s[98:99]
	v_add_u32_e32 v156, 0x800200, v154
	global_load_dwordx4 v[208:211], v156, s[98:99]
	v_add_u32_e32 v156, 0x800400, v154
	global_load_dwordx4 v[212:215], v156, s[98:99]
	v_add_u32_e32 v156, 0x800600, v154
	global_load_dwordx4 v[216:219], v156, s[98:99]
	v_add_u32_e32 v156, 0x801000, v154
	global_load_dwordx4 v[220:223], v156, s[98:99]
	v_add_u32_e32 v156, 0x801200, v154
	global_load_dwordx4 v[224:227], v156, s[98:99]
	v_add_u32_e32 v156, 0x801400, v154
	global_load_dwordx4 v[228:231], v156, s[98:99]
	v_add_u32_e32 v156, 0x801600, v154
	global_load_dwordx4 v[232:235], v156, s[98:99]
	s_waitcnt vmcnt(16)
	s_waitcnt vmcnt(15)
	v_pk_add_f32 v[124:125], v[124:125], v[128:129]
	v_pk_add_f32 v[126:127], v[126:127], v[130:131]
	v_pk_add_f32 v[120:121], v[120:121], v[132:133]
	v_pk_add_f32 v[122:123], v[122:123], v[134:135]
	v_pk_mul_f32 v[124:125], v[160:161], v[124:125]
	v_pk_mul_f32 v[126:127], v[160:161], v[126:127]
	v_pk_mul_f32 v[120:121], v[160:161], v[120:121]
	v_pk_mul_f32 v[122:123], v[160:161], v[122:123]
	v_exp_f32_e32 v124, v124
	v_exp_f32_e32 v125, v125
	v_exp_f32_e32 v126, v126
	v_exp_f32_e32 v127, v127
	v_exp_f32_e32 v120, v120
	v_exp_f32_e32 v121, v121
	v_exp_f32_e32 v122, v122
	v_exp_f32_e32 v123, v123
	v_pk_add_f32 v[124:125], v[124:125], 1.0 op_sel_hi:[1,0]
	v_pk_add_f32 v[126:127], v[126:127], 1.0 op_sel_hi:[1,0]
	v_pk_add_f32 v[120:121], v[120:121], 1.0 op_sel_hi:[1,0]
	v_pk_add_f32 v[122:123], v[122:123], 1.0 op_sel_hi:[1,0]
	v_rcp_f32_e32 v124, v124
	v_rcp_f32_e32 v125, v125
	v_rcp_f32_e32 v126, v126
	v_rcp_f32_e32 v127, v127
	v_rcp_f32_e32 v120, v120
	v_rcp_f32_e32 v121, v121
	v_rcp_f32_e32 v122, v122
	v_rcp_f32_e32 v123, v123
	v_lshlrev_b32_e32 v162, 16, v170
	v_and_b32_e32 v163, 0xffff0000, v170
	v_lshlrev_b32_e32 v164, 16, v171
	v_and_b32_e32 v165, 0xffff0000, v171
	v_lshlrev_b32_e32 v158, 16, v172
	v_and_b32_e32 v159, 0xffff0000, v172
	v_lshlrev_b32_e32 v144, 16, v173
	v_and_b32_e32 v145, 0xffff0000, v173
	v_pk_mul_f32 v[124:125], v[124:125], v[162:163]
	v_pk_mul_f32 v[126:127], v[126:127], v[164:165]
	v_pk_mul_f32 v[120:121], v[120:121], v[158:159]
	v_pk_mul_f32 v[122:123], v[122:123], v[144:145]
	v_cvt_pk_bf16_f32 v170, v124, v125
	v_cvt_pk_bf16_f32 v171, v126, v127
	v_cvt_pk_bf16_f32 v172, v120, v121
	v_cvt_pk_bf16_f32 v173, v122, v123
	v_mov_b32_e32 v156, v155
	global_store_dwordx4 v156, v[170:173], s[100:101]
	s_waitcnt vmcnt(15)
	v_pk_add_f32 v[116:117], v[116:117], v[128:129]
	v_pk_add_f32 v[118:119], v[118:119], v[130:131]
	v_pk_add_f32 v[112:113], v[112:113], v[132:133]
	v_pk_add_f32 v[114:115], v[114:115], v[134:135]
	v_pk_mul_f32 v[116:117], v[160:161], v[116:117]
	v_pk_mul_f32 v[118:119], v[160:161], v[118:119]
	v_pk_mul_f32 v[112:113], v[160:161], v[112:113]
	v_pk_mul_f32 v[114:115], v[160:161], v[114:115]
	v_exp_f32_e32 v116, v116
	v_exp_f32_e32 v117, v117
	v_exp_f32_e32 v118, v118
	v_exp_f32_e32 v119, v119
	v_exp_f32_e32 v112, v112
	v_exp_f32_e32 v113, v113
	v_exp_f32_e32 v114, v114
	v_exp_f32_e32 v115, v115
	v_pk_add_f32 v[116:117], v[116:117], 1.0 op_sel_hi:[1,0]
	v_pk_add_f32 v[118:119], v[118:119], 1.0 op_sel_hi:[1,0]
	v_pk_add_f32 v[112:113], v[112:113], 1.0 op_sel_hi:[1,0]
	v_pk_add_f32 v[114:115], v[114:115], 1.0 op_sel_hi:[1,0]
	v_rcp_f32_e32 v116, v116
	v_rcp_f32_e32 v117, v117
	v_rcp_f32_e32 v118, v118
	v_rcp_f32_e32 v119, v119
	v_rcp_f32_e32 v112, v112
	v_rcp_f32_e32 v113, v113
	v_rcp_f32_e32 v114, v114
	v_rcp_f32_e32 v115, v115
	v_lshlrev_b32_e32 v162, 16, v174
	v_and_b32_e32 v163, 0xffff0000, v174
	v_lshlrev_b32_e32 v164, 16, v175
	v_and_b32_e32 v165, 0xffff0000, v175
	v_lshlrev_b32_e32 v158, 16, v176
	v_and_b32_e32 v159, 0xffff0000, v176
	v_lshlrev_b32_e32 v144, 16, v177
	v_and_b32_e32 v145, 0xffff0000, v177
	v_pk_mul_f32 v[116:117], v[116:117], v[162:163]
	v_pk_mul_f32 v[118:119], v[118:119], v[164:165]
	v_pk_mul_f32 v[112:113], v[112:113], v[158:159]
	v_pk_mul_f32 v[114:115], v[114:115], v[144:145]
	v_cvt_pk_bf16_f32 v174, v116, v117
	v_cvt_pk_bf16_f32 v175, v118, v119
	v_cvt_pk_bf16_f32 v176, v112, v113
	v_cvt_pk_bf16_f32 v177, v114, v115
	v_add_u32_e32 v156, 0x4000, v155
	global_store_dwordx4 v156, v[174:177], s[100:101]
	s_waitcnt vmcnt(15)
	v_pk_add_f32 v[108:109], v[108:109], v[128:129]
	v_pk_add_f32 v[110:111], v[110:111], v[130:131]
	v_pk_add_f32 v[104:105], v[104:105], v[132:133]
	v_pk_add_f32 v[106:107], v[106:107], v[134:135]
	v_pk_mul_f32 v[108:109], v[160:161], v[108:109]
	v_pk_mul_f32 v[110:111], v[160:161], v[110:111]
	v_pk_mul_f32 v[104:105], v[160:161], v[104:105]
	v_pk_mul_f32 v[106:107], v[160:161], v[106:107]
	v_exp_f32_e32 v108, v108
	v_exp_f32_e32 v109, v109
	v_exp_f32_e32 v110, v110
	v_exp_f32_e32 v111, v111
	v_exp_f32_e32 v104, v104
	v_exp_f32_e32 v105, v105
	v_exp_f32_e32 v106, v106
	v_exp_f32_e32 v107, v107
	v_pk_add_f32 v[108:109], v[108:109], 1.0 op_sel_hi:[1,0]
	v_pk_add_f32 v[110:111], v[110:111], 1.0 op_sel_hi:[1,0]
	v_pk_add_f32 v[104:105], v[104:105], 1.0 op_sel_hi:[1,0]
	v_pk_add_f32 v[106:107], v[106:107], 1.0 op_sel_hi:[1,0]
	v_rcp_f32_e32 v108, v108
	v_rcp_f32_e32 v109, v109
	v_rcp_f32_e32 v110, v110
	v_rcp_f32_e32 v111, v111
	v_rcp_f32_e32 v104, v104
	v_rcp_f32_e32 v105, v105
	v_rcp_f32_e32 v106, v106
	v_rcp_f32_e32 v107, v107
	v_lshlrev_b32_e32 v162, 16, v178
	v_and_b32_e32 v163, 0xffff0000, v178
	v_lshlrev_b32_e32 v164, 16, v179
	v_and_b32_e32 v165, 0xffff0000, v179
	v_lshlrev_b32_e32 v158, 16, v180
	v_and_b32_e32 v159, 0xffff0000, v180
	v_lshlrev_b32_e32 v144, 16, v181
	v_and_b32_e32 v145, 0xffff0000, v181
	v_pk_mul_f32 v[108:109], v[108:109], v[162:163]
	v_pk_mul_f32 v[110:111], v[110:111], v[164:165]
	v_pk_mul_f32 v[104:105], v[104:105], v[158:159]
	v_pk_mul_f32 v[106:107], v[106:107], v[144:145]
	v_cvt_pk_bf16_f32 v178, v108, v109
	v_cvt_pk_bf16_f32 v179, v110, v111
	v_cvt_pk_bf16_f32 v180, v104, v105
	v_cvt_pk_bf16_f32 v181, v106, v107
	v_add_u32_e32 v156, 0x8000, v155
	global_store_dwordx4 v156, v[178:181], s[100:101]
	s_waitcnt vmcnt(15)
	v_pk_add_f32 v[100:101], v[100:101], v[128:129]
	v_pk_add_f32 v[102:103], v[102:103], v[130:131]
	v_pk_add_f32 v[96:97], v[96:97], v[132:133]
	v_pk_add_f32 v[98:99], v[98:99], v[134:135]
	v_pk_mul_f32 v[100:101], v[160:161], v[100:101]
	v_pk_mul_f32 v[102:103], v[160:161], v[102:103]
	v_pk_mul_f32 v[96:97], v[160:161], v[96:97]
	v_pk_mul_f32 v[98:99], v[160:161], v[98:99]
	v_exp_f32_e32 v100, v100
	v_exp_f32_e32 v101, v101
	v_exp_f32_e32 v102, v102
	v_exp_f32_e32 v103, v103
	v_exp_f32_e32 v96, v96
	v_exp_f32_e32 v97, v97
	v_exp_f32_e32 v98, v98
	v_exp_f32_e32 v99, v99
	v_pk_add_f32 v[100:101], v[100:101], 1.0 op_sel_hi:[1,0]
	v_pk_add_f32 v[102:103], v[102:103], 1.0 op_sel_hi:[1,0]
	v_pk_add_f32 v[96:97], v[96:97], 1.0 op_sel_hi:[1,0]
	v_pk_add_f32 v[98:99], v[98:99], 1.0 op_sel_hi:[1,0]
	v_rcp_f32_e32 v100, v100
	v_rcp_f32_e32 v101, v101
	v_rcp_f32_e32 v102, v102
	v_rcp_f32_e32 v103, v103
	v_rcp_f32_e32 v96, v96
	v_rcp_f32_e32 v97, v97
	v_rcp_f32_e32 v98, v98
	v_rcp_f32_e32 v99, v99
	v_lshlrev_b32_e32 v162, 16, v182
	v_and_b32_e32 v163, 0xffff0000, v182
	v_lshlrev_b32_e32 v164, 16, v183
	v_and_b32_e32 v165, 0xffff0000, v183
	v_lshlrev_b32_e32 v158, 16, v184
	v_and_b32_e32 v159, 0xffff0000, v184
	v_lshlrev_b32_e32 v144, 16, v185
	v_and_b32_e32 v145, 0xffff0000, v185
	v_pk_mul_f32 v[100:101], v[100:101], v[162:163]
	v_pk_mul_f32 v[102:103], v[102:103], v[164:165]
	v_pk_mul_f32 v[96:97], v[96:97], v[158:159]
	v_pk_mul_f32 v[98:99], v[98:99], v[144:145]
	v_cvt_pk_bf16_f32 v182, v100, v101
	v_cvt_pk_bf16_f32 v183, v102, v103
	v_cvt_pk_bf16_f32 v184, v96, v97
	v_cvt_pk_bf16_f32 v185, v98, v99
	v_add_u32_e32 v156, 0xc000, v155
	global_store_dwordx4 v156, v[182:185], s[100:101]
	s_waitcnt vmcnt(15)
	v_pk_add_f32 v[92:93], v[92:93], v[128:129]
	v_pk_add_f32 v[94:95], v[94:95], v[130:131]
	v_pk_add_f32 v[88:89], v[88:89], v[132:133]
	v_pk_add_f32 v[90:91], v[90:91], v[134:135]
	v_pk_mul_f32 v[92:93], v[160:161], v[92:93]
	v_pk_mul_f32 v[94:95], v[160:161], v[94:95]
	v_pk_mul_f32 v[88:89], v[160:161], v[88:89]
	v_pk_mul_f32 v[90:91], v[160:161], v[90:91]
	v_exp_f32_e32 v92, v92
	v_exp_f32_e32 v93, v93
	v_exp_f32_e32 v94, v94
	v_exp_f32_e32 v95, v95
	v_exp_f32_e32 v88, v88
	v_exp_f32_e32 v89, v89
	v_exp_f32_e32 v90, v90
	v_exp_f32_e32 v91, v91
	v_pk_add_f32 v[92:93], v[92:93], 1.0 op_sel_hi:[1,0]
	v_pk_add_f32 v[94:95], v[94:95], 1.0 op_sel_hi:[1,0]
	v_pk_add_f32 v[88:89], v[88:89], 1.0 op_sel_hi:[1,0]
	v_pk_add_f32 v[90:91], v[90:91], 1.0 op_sel_hi:[1,0]
	v_rcp_f32_e32 v92, v92
	v_rcp_f32_e32 v93, v93
	v_rcp_f32_e32 v94, v94
	v_rcp_f32_e32 v95, v95
	v_rcp_f32_e32 v88, v88
	v_rcp_f32_e32 v89, v89
	v_rcp_f32_e32 v90, v90
	v_rcp_f32_e32 v91, v91
	v_lshlrev_b32_e32 v162, 16, v186
	v_and_b32_e32 v163, 0xffff0000, v186
	v_lshlrev_b32_e32 v164, 16, v187
	v_and_b32_e32 v165, 0xffff0000, v187
	v_lshlrev_b32_e32 v158, 16, v188
	v_and_b32_e32 v159, 0xffff0000, v188
	v_lshlrev_b32_e32 v144, 16, v189
	v_and_b32_e32 v145, 0xffff0000, v189
	v_pk_mul_f32 v[92:93], v[92:93], v[162:163]
	v_pk_mul_f32 v[94:95], v[94:95], v[164:165]
	v_pk_mul_f32 v[88:89], v[88:89], v[158:159]
	v_pk_mul_f32 v[90:91], v[90:91], v[144:145]
	v_cvt_pk_bf16_f32 v186, v92, v93
	v_cvt_pk_bf16_f32 v187, v94, v95
	v_cvt_pk_bf16_f32 v188, v88, v89
	v_cvt_pk_bf16_f32 v189, v90, v91
	v_add_u32_e32 v156, 0x20000, v155
	global_store_dwordx4 v156, v[186:189], s[100:101]
	s_waitcnt vmcnt(15)
	v_pk_add_f32 v[84:85], v[84:85], v[128:129]
	v_pk_add_f32 v[86:87], v[86:87], v[130:131]
	v_pk_add_f32 v[80:81], v[80:81], v[132:133]
	v_pk_add_f32 v[82:83], v[82:83], v[134:135]
	v_pk_mul_f32 v[84:85], v[160:161], v[84:85]
	v_pk_mul_f32 v[86:87], v[160:161], v[86:87]
	v_pk_mul_f32 v[80:81], v[160:161], v[80:81]
	v_pk_mul_f32 v[82:83], v[160:161], v[82:83]
	v_exp_f32_e32 v84, v84
	v_exp_f32_e32 v85, v85
	v_exp_f32_e32 v86, v86
	v_exp_f32_e32 v87, v87
	v_exp_f32_e32 v80, v80
	v_exp_f32_e32 v81, v81
	v_exp_f32_e32 v82, v82
	v_exp_f32_e32 v83, v83
	v_pk_add_f32 v[84:85], v[84:85], 1.0 op_sel_hi:[1,0]
	v_pk_add_f32 v[86:87], v[86:87], 1.0 op_sel_hi:[1,0]
	v_pk_add_f32 v[80:81], v[80:81], 1.0 op_sel_hi:[1,0]
	v_pk_add_f32 v[82:83], v[82:83], 1.0 op_sel_hi:[1,0]
	v_rcp_f32_e32 v84, v84
	v_rcp_f32_e32 v85, v85
	v_rcp_f32_e32 v86, v86
	v_rcp_f32_e32 v87, v87
	v_rcp_f32_e32 v80, v80
	v_rcp_f32_e32 v81, v81
	v_rcp_f32_e32 v82, v82
	v_rcp_f32_e32 v83, v83
	v_lshlrev_b32_e32 v162, 16, v192
	v_and_b32_e32 v163, 0xffff0000, v192
	v_lshlrev_b32_e32 v164, 16, v193
	v_and_b32_e32 v165, 0xffff0000, v193
	v_lshlrev_b32_e32 v158, 16, v194
	v_and_b32_e32 v159, 0xffff0000, v194
	v_lshlrev_b32_e32 v144, 16, v195
	v_and_b32_e32 v145, 0xffff0000, v195
	v_pk_mul_f32 v[84:85], v[84:85], v[162:163]
	v_pk_mul_f32 v[86:87], v[86:87], v[164:165]
	v_pk_mul_f32 v[80:81], v[80:81], v[158:159]
	v_pk_mul_f32 v[82:83], v[82:83], v[144:145]
	v_cvt_pk_bf16_f32 v192, v84, v85
	v_cvt_pk_bf16_f32 v193, v86, v87
	v_cvt_pk_bf16_f32 v194, v80, v81
	v_cvt_pk_bf16_f32 v195, v82, v83
	v_add_u32_e32 v156, 0x24000, v155
	global_store_dwordx4 v156, v[192:195], s[100:101]
	s_waitcnt vmcnt(15)
	v_pk_add_f32 v[76:77], v[76:77], v[128:129]
	v_pk_add_f32 v[78:79], v[78:79], v[130:131]
	v_pk_add_f32 v[72:73], v[72:73], v[132:133]
	v_pk_add_f32 v[74:75], v[74:75], v[134:135]
	v_pk_mul_f32 v[76:77], v[160:161], v[76:77]
	v_pk_mul_f32 v[78:79], v[160:161], v[78:79]
	v_pk_mul_f32 v[72:73], v[160:161], v[72:73]
	v_pk_mul_f32 v[74:75], v[160:161], v[74:75]
	v_exp_f32_e32 v76, v76
	v_exp_f32_e32 v77, v77
	v_exp_f32_e32 v78, v78
	v_exp_f32_e32 v79, v79
	v_exp_f32_e32 v72, v72
	v_exp_f32_e32 v73, v73
	v_exp_f32_e32 v74, v74
	v_exp_f32_e32 v75, v75
	v_pk_add_f32 v[76:77], v[76:77], 1.0 op_sel_hi:[1,0]
	v_pk_add_f32 v[78:79], v[78:79], 1.0 op_sel_hi:[1,0]
	v_pk_add_f32 v[72:73], v[72:73], 1.0 op_sel_hi:[1,0]
	v_pk_add_f32 v[74:75], v[74:75], 1.0 op_sel_hi:[1,0]
	v_rcp_f32_e32 v76, v76
	v_rcp_f32_e32 v77, v77
	v_rcp_f32_e32 v78, v78
	v_rcp_f32_e32 v79, v79
	v_rcp_f32_e32 v72, v72
	v_rcp_f32_e32 v73, v73
	v_rcp_f32_e32 v74, v74
	v_rcp_f32_e32 v75, v75
	v_lshlrev_b32_e32 v162, 16, v196
	v_and_b32_e32 v163, 0xffff0000, v196
	v_lshlrev_b32_e32 v164, 16, v197
	v_and_b32_e32 v165, 0xffff0000, v197
	v_lshlrev_b32_e32 v158, 16, v198
	v_and_b32_e32 v159, 0xffff0000, v198
	v_lshlrev_b32_e32 v144, 16, v199
	v_and_b32_e32 v145, 0xffff0000, v199
	v_pk_mul_f32 v[76:77], v[76:77], v[162:163]
	v_pk_mul_f32 v[78:79], v[78:79], v[164:165]
	v_pk_mul_f32 v[72:73], v[72:73], v[158:159]
	v_pk_mul_f32 v[74:75], v[74:75], v[144:145]
	v_cvt_pk_bf16_f32 v196, v76, v77
	v_cvt_pk_bf16_f32 v197, v78, v79
	v_cvt_pk_bf16_f32 v198, v72, v73
	v_cvt_pk_bf16_f32 v199, v74, v75
	v_add_u32_e32 v156, 0x28000, v155
	global_store_dwordx4 v156, v[196:199], s[100:101]
	s_waitcnt vmcnt(15)
	v_pk_add_f32 v[68:69], v[68:69], v[128:129]
	v_pk_add_f32 v[70:71], v[70:71], v[130:131]
	v_pk_add_f32 v[64:65], v[64:65], v[132:133]
	v_pk_add_f32 v[66:67], v[66:67], v[134:135]
	v_pk_mul_f32 v[68:69], v[160:161], v[68:69]
	v_pk_mul_f32 v[70:71], v[160:161], v[70:71]
	v_pk_mul_f32 v[64:65], v[160:161], v[64:65]
	v_pk_mul_f32 v[66:67], v[160:161], v[66:67]
	v_exp_f32_e32 v68, v68
	v_exp_f32_e32 v69, v69
	v_exp_f32_e32 v70, v70
	v_exp_f32_e32 v71, v71
	v_exp_f32_e32 v64, v64
	v_exp_f32_e32 v65, v65
	v_exp_f32_e32 v66, v66
	v_exp_f32_e32 v67, v67
	v_pk_add_f32 v[68:69], v[68:69], 1.0 op_sel_hi:[1,0]
	v_pk_add_f32 v[70:71], v[70:71], 1.0 op_sel_hi:[1,0]
	v_pk_add_f32 v[64:65], v[64:65], 1.0 op_sel_hi:[1,0]
	v_pk_add_f32 v[66:67], v[66:67], 1.0 op_sel_hi:[1,0]
	v_rcp_f32_e32 v68, v68
	v_rcp_f32_e32 v69, v69
	v_rcp_f32_e32 v70, v70
	v_rcp_f32_e32 v71, v71
	v_rcp_f32_e32 v64, v64
	v_rcp_f32_e32 v65, v65
	v_rcp_f32_e32 v66, v66
	v_rcp_f32_e32 v67, v67
	v_lshlrev_b32_e32 v162, 16, v200
	v_and_b32_e32 v163, 0xffff0000, v200
	v_lshlrev_b32_e32 v164, 16, v201
	v_and_b32_e32 v165, 0xffff0000, v201
	v_lshlrev_b32_e32 v158, 16, v202
	v_and_b32_e32 v159, 0xffff0000, v202
	v_lshlrev_b32_e32 v144, 16, v203
	v_and_b32_e32 v145, 0xffff0000, v203
	v_pk_mul_f32 v[68:69], v[68:69], v[162:163]
	v_pk_mul_f32 v[70:71], v[70:71], v[164:165]
	v_pk_mul_f32 v[64:65], v[64:65], v[158:159]
	v_pk_mul_f32 v[66:67], v[66:67], v[144:145]
	v_cvt_pk_bf16_f32 v200, v68, v69
	v_cvt_pk_bf16_f32 v201, v70, v71
	v_cvt_pk_bf16_f32 v202, v64, v65
	v_cvt_pk_bf16_f32 v203, v66, v67
	v_add_u32_e32 v156, 0x2c000, v155
	global_store_dwordx4 v156, v[200:203], s[100:101]
	global_load_dwordx4 v[128:131], v157, s[10:11] offset:512
	global_load_dwordx4 v[132:135], v157, s[10:11] offset:528
	s_waitcnt vmcnt(0)
	v_pk_add_f32 v[60:61], v[60:61], v[128:129]
	v_pk_add_f32 v[62:63], v[62:63], v[130:131]
	v_pk_add_f32 v[56:57], v[56:57], v[132:133]
	v_pk_add_f32 v[58:59], v[58:59], v[134:135]
	v_pk_mul_f32 v[60:61], v[160:161], v[60:61]
	v_pk_mul_f32 v[62:63], v[160:161], v[62:63]
	v_pk_mul_f32 v[56:57], v[160:161], v[56:57]
	v_pk_mul_f32 v[58:59], v[160:161], v[58:59]
	v_exp_f32_e32 v60, v60
	v_exp_f32_e32 v61, v61
	v_exp_f32_e32 v62, v62
	v_exp_f32_e32 v63, v63
	v_exp_f32_e32 v56, v56
	v_exp_f32_e32 v57, v57
	v_exp_f32_e32 v58, v58
	v_exp_f32_e32 v59, v59
	v_pk_add_f32 v[60:61], v[60:61], 1.0 op_sel_hi:[1,0]
	v_pk_add_f32 v[62:63], v[62:63], 1.0 op_sel_hi:[1,0]
	v_pk_add_f32 v[56:57], v[56:57], 1.0 op_sel_hi:[1,0]
	v_pk_add_f32 v[58:59], v[58:59], 1.0 op_sel_hi:[1,0]
	v_rcp_f32_e32 v60, v60
	v_rcp_f32_e32 v61, v61
	v_rcp_f32_e32 v62, v62
	v_rcp_f32_e32 v63, v63
	v_rcp_f32_e32 v56, v56
	v_rcp_f32_e32 v57, v57
	v_rcp_f32_e32 v58, v58
	v_rcp_f32_e32 v59, v59
	v_lshlrev_b32_e32 v162, 16, v204
	v_and_b32_e32 v163, 0xffff0000, v204
	v_lshlrev_b32_e32 v164, 16, v205
	v_and_b32_e32 v165, 0xffff0000, v205
	v_lshlrev_b32_e32 v158, 16, v206
	v_and_b32_e32 v159, 0xffff0000, v206
	v_lshlrev_b32_e32 v144, 16, v207
	v_and_b32_e32 v145, 0xffff0000, v207
	v_pk_mul_f32 v[60:61], v[60:61], v[162:163]
	v_pk_mul_f32 v[62:63], v[62:63], v[164:165]
	v_pk_mul_f32 v[56:57], v[56:57], v[158:159]
	v_pk_mul_f32 v[58:59], v[58:59], v[144:145]
	v_cvt_pk_bf16_f32 v204, v60, v61
	v_cvt_pk_bf16_f32 v205, v62, v63
	v_cvt_pk_bf16_f32 v206, v56, v57
	v_cvt_pk_bf16_f32 v207, v58, v59
	v_add_u32_e32 v156, 0x100, v155
	global_store_dwordx4 v156, v[204:207], s[100:101]
	s_waitcnt vmcnt(17)
	v_pk_add_f32 v[52:53], v[52:53], v[128:129]
	v_pk_add_f32 v[54:55], v[54:55], v[130:131]
	v_pk_add_f32 v[48:49], v[48:49], v[132:133]
	v_pk_add_f32 v[50:51], v[50:51], v[134:135]
	v_pk_mul_f32 v[52:53], v[160:161], v[52:53]
	v_pk_mul_f32 v[54:55], v[160:161], v[54:55]
	v_pk_mul_f32 v[48:49], v[160:161], v[48:49]
	v_pk_mul_f32 v[50:51], v[160:161], v[50:51]
	v_exp_f32_e32 v52, v52
	v_exp_f32_e32 v53, v53
	v_exp_f32_e32 v54, v54
	v_exp_f32_e32 v55, v55
	v_exp_f32_e32 v48, v48
	v_exp_f32_e32 v49, v49
	v_exp_f32_e32 v50, v50
	v_exp_f32_e32 v51, v51
	v_pk_add_f32 v[52:53], v[52:53], 1.0 op_sel_hi:[1,0]
	v_pk_add_f32 v[54:55], v[54:55], 1.0 op_sel_hi:[1,0]
	v_pk_add_f32 v[48:49], v[48:49], 1.0 op_sel_hi:[1,0]
	v_pk_add_f32 v[50:51], v[50:51], 1.0 op_sel_hi:[1,0]
	v_rcp_f32_e32 v52, v52
	v_rcp_f32_e32 v53, v53
	v_rcp_f32_e32 v54, v54
	v_rcp_f32_e32 v55, v55
	v_rcp_f32_e32 v48, v48
	v_rcp_f32_e32 v49, v49
	v_rcp_f32_e32 v50, v50
	v_rcp_f32_e32 v51, v51
	v_lshlrev_b32_e32 v162, 16, v208
	v_and_b32_e32 v163, 0xffff0000, v208
	v_lshlrev_b32_e32 v164, 16, v209
	v_and_b32_e32 v165, 0xffff0000, v209
	v_lshlrev_b32_e32 v158, 16, v210
	v_and_b32_e32 v159, 0xffff0000, v210
	v_lshlrev_b32_e32 v144, 16, v211
	v_and_b32_e32 v145, 0xffff0000, v211
	v_pk_mul_f32 v[52:53], v[52:53], v[162:163]
	v_pk_mul_f32 v[54:55], v[54:55], v[164:165]
	v_pk_mul_f32 v[48:49], v[48:49], v[158:159]
	v_pk_mul_f32 v[50:51], v[50:51], v[144:145]
	v_cvt_pk_bf16_f32 v208, v52, v53
	v_cvt_pk_bf16_f32 v209, v54, v55
	v_cvt_pk_bf16_f32 v210, v48, v49
	v_cvt_pk_bf16_f32 v211, v50, v51
	v_add_u32_e32 v156, 0x4100, v155
	global_store_dwordx4 v156, v[208:211], s[100:101]
	s_waitcnt vmcnt(17)
	v_pk_add_f32 v[44:45], v[44:45], v[128:129]
	v_pk_add_f32 v[46:47], v[46:47], v[130:131]
	v_pk_add_f32 v[40:41], v[40:41], v[132:133]
	v_pk_add_f32 v[42:43], v[42:43], v[134:135]
	v_pk_mul_f32 v[44:45], v[160:161], v[44:45]
	v_pk_mul_f32 v[46:47], v[160:161], v[46:47]
	v_pk_mul_f32 v[40:41], v[160:161], v[40:41]
	v_pk_mul_f32 v[42:43], v[160:161], v[42:43]
	v_exp_f32_e32 v44, v44
	v_exp_f32_e32 v45, v45
	v_exp_f32_e32 v46, v46
	v_exp_f32_e32 v47, v47
	v_exp_f32_e32 v40, v40
	v_exp_f32_e32 v41, v41
	v_exp_f32_e32 v42, v42
	v_exp_f32_e32 v43, v43
	v_pk_add_f32 v[44:45], v[44:45], 1.0 op_sel_hi:[1,0]
	v_pk_add_f32 v[46:47], v[46:47], 1.0 op_sel_hi:[1,0]
	v_pk_add_f32 v[40:41], v[40:41], 1.0 op_sel_hi:[1,0]
	v_pk_add_f32 v[42:43], v[42:43], 1.0 op_sel_hi:[1,0]
	v_rcp_f32_e32 v44, v44
	v_rcp_f32_e32 v45, v45
	v_rcp_f32_e32 v46, v46
	v_rcp_f32_e32 v47, v47
	v_rcp_f32_e32 v40, v40
	v_rcp_f32_e32 v41, v41
	v_rcp_f32_e32 v42, v42
	v_rcp_f32_e32 v43, v43
	v_lshlrev_b32_e32 v162, 16, v212
	v_and_b32_e32 v163, 0xffff0000, v212
	v_lshlrev_b32_e32 v164, 16, v213
	v_and_b32_e32 v165, 0xffff0000, v213
	v_lshlrev_b32_e32 v158, 16, v214
	v_and_b32_e32 v159, 0xffff0000, v214
	v_lshlrev_b32_e32 v144, 16, v215
	v_and_b32_e32 v145, 0xffff0000, v215
	v_pk_mul_f32 v[44:45], v[44:45], v[162:163]
	v_pk_mul_f32 v[46:47], v[46:47], v[164:165]
	v_pk_mul_f32 v[40:41], v[40:41], v[158:159]
	v_pk_mul_f32 v[42:43], v[42:43], v[144:145]
	v_cvt_pk_bf16_f32 v212, v44, v45
	v_cvt_pk_bf16_f32 v213, v46, v47
	v_cvt_pk_bf16_f32 v214, v40, v41
	v_cvt_pk_bf16_f32 v215, v42, v43
	v_add_u32_e32 v156, 0x8100, v155
	global_store_dwordx4 v156, v[212:215], s[100:101]
	s_waitcnt vmcnt(17)
	v_pk_add_f32 v[36:37], v[36:37], v[128:129]
	v_pk_add_f32 v[38:39], v[38:39], v[130:131]
	v_pk_add_f32 v[32:33], v[32:33], v[132:133]
	v_pk_add_f32 v[34:35], v[34:35], v[134:135]
	v_pk_mul_f32 v[36:37], v[160:161], v[36:37]
	v_pk_mul_f32 v[38:39], v[160:161], v[38:39]
	v_pk_mul_f32 v[32:33], v[160:161], v[32:33]
	v_pk_mul_f32 v[34:35], v[160:161], v[34:35]
	v_exp_f32_e32 v36, v36
	v_exp_f32_e32 v37, v37
	v_exp_f32_e32 v38, v38
	v_exp_f32_e32 v39, v39
	v_exp_f32_e32 v32, v32
	v_exp_f32_e32 v33, v33
	v_exp_f32_e32 v34, v34
	v_exp_f32_e32 v35, v35
	v_pk_add_f32 v[36:37], v[36:37], 1.0 op_sel_hi:[1,0]
	v_pk_add_f32 v[38:39], v[38:39], 1.0 op_sel_hi:[1,0]
	v_pk_add_f32 v[32:33], v[32:33], 1.0 op_sel_hi:[1,0]
	v_pk_add_f32 v[34:35], v[34:35], 1.0 op_sel_hi:[1,0]
	v_rcp_f32_e32 v36, v36
	v_rcp_f32_e32 v37, v37
	v_rcp_f32_e32 v38, v38
	v_rcp_f32_e32 v39, v39
	v_rcp_f32_e32 v32, v32
	v_rcp_f32_e32 v33, v33
	v_rcp_f32_e32 v34, v34
	v_rcp_f32_e32 v35, v35
	v_lshlrev_b32_e32 v162, 16, v216
	v_and_b32_e32 v163, 0xffff0000, v216
	v_lshlrev_b32_e32 v164, 16, v217
	v_and_b32_e32 v165, 0xffff0000, v217
	v_lshlrev_b32_e32 v158, 16, v218
	v_and_b32_e32 v159, 0xffff0000, v218
	v_lshlrev_b32_e32 v144, 16, v219
	v_and_b32_e32 v145, 0xffff0000, v219
	v_pk_mul_f32 v[36:37], v[36:37], v[162:163]
	v_pk_mul_f32 v[38:39], v[38:39], v[164:165]
	v_pk_mul_f32 v[32:33], v[32:33], v[158:159]
	v_pk_mul_f32 v[34:35], v[34:35], v[144:145]
	v_cvt_pk_bf16_f32 v216, v36, v37
	v_cvt_pk_bf16_f32 v217, v38, v39
	v_cvt_pk_bf16_f32 v218, v32, v33
	v_cvt_pk_bf16_f32 v219, v34, v35
	v_add_u32_e32 v156, 0xc100, v155
	global_store_dwordx4 v156, v[216:219], s[100:101]
	s_waitcnt vmcnt(17)
	v_pk_add_f32 v[28:29], v[28:29], v[128:129]
	v_pk_add_f32 v[30:31], v[30:31], v[130:131]
	v_pk_add_f32 v[24:25], v[24:25], v[132:133]
	v_pk_add_f32 v[26:27], v[26:27], v[134:135]
	v_pk_mul_f32 v[28:29], v[160:161], v[28:29]
	v_pk_mul_f32 v[30:31], v[160:161], v[30:31]
	v_pk_mul_f32 v[24:25], v[160:161], v[24:25]
	v_pk_mul_f32 v[26:27], v[160:161], v[26:27]
	v_exp_f32_e32 v28, v28
	v_exp_f32_e32 v29, v29
	v_exp_f32_e32 v30, v30
	v_exp_f32_e32 v31, v31
	v_exp_f32_e32 v24, v24
	v_exp_f32_e32 v25, v25
	v_exp_f32_e32 v26, v26
	v_exp_f32_e32 v27, v27
	v_pk_add_f32 v[28:29], v[28:29], 1.0 op_sel_hi:[1,0]
	v_pk_add_f32 v[30:31], v[30:31], 1.0 op_sel_hi:[1,0]
	v_pk_add_f32 v[24:25], v[24:25], 1.0 op_sel_hi:[1,0]
	v_pk_add_f32 v[26:27], v[26:27], 1.0 op_sel_hi:[1,0]
	v_rcp_f32_e32 v28, v28
	v_rcp_f32_e32 v29, v29
	v_rcp_f32_e32 v30, v30
	v_rcp_f32_e32 v31, v31
	v_rcp_f32_e32 v24, v24
	v_rcp_f32_e32 v25, v25
	v_rcp_f32_e32 v26, v26
	v_rcp_f32_e32 v27, v27
	v_lshlrev_b32_e32 v162, 16, v220
	v_and_b32_e32 v163, 0xffff0000, v220
	v_lshlrev_b32_e32 v164, 16, v221
	v_and_b32_e32 v165, 0xffff0000, v221
	v_lshlrev_b32_e32 v158, 16, v222
	v_and_b32_e32 v159, 0xffff0000, v222
	v_lshlrev_b32_e32 v144, 16, v223
	v_and_b32_e32 v145, 0xffff0000, v223
	v_pk_mul_f32 v[28:29], v[28:29], v[162:163]
	v_pk_mul_f32 v[30:31], v[30:31], v[164:165]
	v_pk_mul_f32 v[24:25], v[24:25], v[158:159]
	v_pk_mul_f32 v[26:27], v[26:27], v[144:145]
	v_cvt_pk_bf16_f32 v220, v28, v29
	v_cvt_pk_bf16_f32 v221, v30, v31
	v_cvt_pk_bf16_f32 v222, v24, v25
	v_cvt_pk_bf16_f32 v223, v26, v27
	v_add_u32_e32 v156, 0x20100, v155
	global_store_dwordx4 v156, v[220:223], s[100:101]
	s_waitcnt vmcnt(17)
	v_pk_add_f32 v[20:21], v[20:21], v[128:129]
	v_pk_add_f32 v[22:23], v[22:23], v[130:131]
	v_pk_add_f32 v[16:17], v[16:17], v[132:133]
	v_pk_add_f32 v[18:19], v[18:19], v[134:135]
	v_pk_mul_f32 v[20:21], v[160:161], v[20:21]
	v_pk_mul_f32 v[22:23], v[160:161], v[22:23]
	v_pk_mul_f32 v[16:17], v[160:161], v[16:17]
	v_pk_mul_f32 v[18:19], v[160:161], v[18:19]
	v_exp_f32_e32 v20, v20
	v_exp_f32_e32 v21, v21
	v_exp_f32_e32 v22, v22
	v_exp_f32_e32 v23, v23
	v_exp_f32_e32 v16, v16
	v_exp_f32_e32 v17, v17
	v_exp_f32_e32 v18, v18
	v_exp_f32_e32 v19, v19
	v_pk_add_f32 v[20:21], v[20:21], 1.0 op_sel_hi:[1,0]
	v_pk_add_f32 v[22:23], v[22:23], 1.0 op_sel_hi:[1,0]
	v_pk_add_f32 v[16:17], v[16:17], 1.0 op_sel_hi:[1,0]
	v_pk_add_f32 v[18:19], v[18:19], 1.0 op_sel_hi:[1,0]
	v_rcp_f32_e32 v20, v20
	v_rcp_f32_e32 v21, v21
	v_rcp_f32_e32 v22, v22
	v_rcp_f32_e32 v23, v23
	v_rcp_f32_e32 v16, v16
	v_rcp_f32_e32 v17, v17
	v_rcp_f32_e32 v18, v18
	v_rcp_f32_e32 v19, v19
	v_lshlrev_b32_e32 v162, 16, v224
	v_and_b32_e32 v163, 0xffff0000, v224
	v_lshlrev_b32_e32 v164, 16, v225
	v_and_b32_e32 v165, 0xffff0000, v225
	v_lshlrev_b32_e32 v158, 16, v226
	v_and_b32_e32 v159, 0xffff0000, v226
	v_lshlrev_b32_e32 v144, 16, v227
	v_and_b32_e32 v145, 0xffff0000, v227
	v_pk_mul_f32 v[20:21], v[20:21], v[162:163]
	v_pk_mul_f32 v[22:23], v[22:23], v[164:165]
	v_pk_mul_f32 v[16:17], v[16:17], v[158:159]
	v_pk_mul_f32 v[18:19], v[18:19], v[144:145]
	v_cvt_pk_bf16_f32 v224, v20, v21
	v_cvt_pk_bf16_f32 v225, v22, v23
	v_cvt_pk_bf16_f32 v226, v16, v17
	v_cvt_pk_bf16_f32 v227, v18, v19
	v_add_u32_e32 v156, 0x24100, v155
	global_store_dwordx4 v156, v[224:227], s[100:101]
	s_waitcnt vmcnt(17)
	v_pk_add_f32 v[12:13], v[12:13], v[128:129]
	v_pk_add_f32 v[14:15], v[14:15], v[130:131]
	v_pk_add_f32 v[8:9], v[8:9], v[132:133]
	v_pk_add_f32 v[10:11], v[10:11], v[134:135]
	v_pk_mul_f32 v[12:13], v[160:161], v[12:13]
	v_pk_mul_f32 v[14:15], v[160:161], v[14:15]
	v_pk_mul_f32 v[8:9], v[160:161], v[8:9]
	v_pk_mul_f32 v[10:11], v[160:161], v[10:11]
	v_exp_f32_e32 v12, v12
	v_exp_f32_e32 v13, v13
	v_exp_f32_e32 v14, v14
	v_exp_f32_e32 v15, v15
	v_exp_f32_e32 v8, v8
	v_exp_f32_e32 v9, v9
	v_exp_f32_e32 v10, v10
	v_exp_f32_e32 v11, v11
	v_pk_add_f32 v[12:13], v[12:13], 1.0 op_sel_hi:[1,0]
	v_pk_add_f32 v[14:15], v[14:15], 1.0 op_sel_hi:[1,0]
	v_pk_add_f32 v[8:9], v[8:9], 1.0 op_sel_hi:[1,0]
	v_pk_add_f32 v[10:11], v[10:11], 1.0 op_sel_hi:[1,0]
	v_rcp_f32_e32 v12, v12
	v_rcp_f32_e32 v13, v13
	v_rcp_f32_e32 v14, v14
	v_rcp_f32_e32 v15, v15
	v_rcp_f32_e32 v8, v8
	v_rcp_f32_e32 v9, v9
	v_rcp_f32_e32 v10, v10
	v_rcp_f32_e32 v11, v11
	v_lshlrev_b32_e32 v162, 16, v228
	v_and_b32_e32 v163, 0xffff0000, v228
	v_lshlrev_b32_e32 v164, 16, v229
	v_and_b32_e32 v165, 0xffff0000, v229
	v_lshlrev_b32_e32 v158, 16, v230
	v_and_b32_e32 v159, 0xffff0000, v230
	v_lshlrev_b32_e32 v144, 16, v231
	v_and_b32_e32 v145, 0xffff0000, v231
	v_pk_mul_f32 v[12:13], v[12:13], v[162:163]
	v_pk_mul_f32 v[14:15], v[14:15], v[164:165]
	v_pk_mul_f32 v[8:9], v[8:9], v[158:159]
	v_pk_mul_f32 v[10:11], v[10:11], v[144:145]
	v_cvt_pk_bf16_f32 v228, v12, v13
	v_cvt_pk_bf16_f32 v229, v14, v15
	v_cvt_pk_bf16_f32 v230, v8, v9
	v_cvt_pk_bf16_f32 v231, v10, v11
	v_add_u32_e32 v156, 0x28100, v155
	global_store_dwordx4 v156, v[228:231], s[100:101]
	s_waitcnt vmcnt(17)
	v_pk_add_f32 v[4:5], v[4:5], v[128:129]
	v_pk_add_f32 v[6:7], v[6:7], v[130:131]
	v_pk_add_f32 v[0:1], v[0:1], v[132:133]
	v_pk_add_f32 v[2:3], v[2:3], v[134:135]
	v_pk_mul_f32 v[4:5], v[160:161], v[4:5]
	v_pk_mul_f32 v[6:7], v[160:161], v[6:7]
	v_pk_mul_f32 v[0:1], v[160:161], v[0:1]
	v_pk_mul_f32 v[2:3], v[160:161], v[2:3]
	v_exp_f32_e32 v4, v4
	v_exp_f32_e32 v5, v5
	v_exp_f32_e32 v6, v6
	v_exp_f32_e32 v7, v7
	v_exp_f32_e32 v0, v0
	v_exp_f32_e32 v1, v1
	v_exp_f32_e32 v2, v2
	v_exp_f32_e32 v3, v3
	v_pk_add_f32 v[4:5], v[4:5], 1.0 op_sel_hi:[1,0]
	v_pk_add_f32 v[6:7], v[6:7], 1.0 op_sel_hi:[1,0]
	v_pk_add_f32 v[0:1], v[0:1], 1.0 op_sel_hi:[1,0]
	v_pk_add_f32 v[2:3], v[2:3], 1.0 op_sel_hi:[1,0]
	v_rcp_f32_e32 v4, v4
	v_rcp_f32_e32 v5, v5
	v_rcp_f32_e32 v6, v6
	v_rcp_f32_e32 v7, v7
	v_rcp_f32_e32 v0, v0
	v_rcp_f32_e32 v1, v1
	v_rcp_f32_e32 v2, v2
	v_rcp_f32_e32 v3, v3
	v_lshlrev_b32_e32 v162, 16, v232
	v_and_b32_e32 v163, 0xffff0000, v232
	v_lshlrev_b32_e32 v164, 16, v233
	v_and_b32_e32 v165, 0xffff0000, v233
	v_lshlrev_b32_e32 v158, 16, v234
	v_and_b32_e32 v159, 0xffff0000, v234
	v_lshlrev_b32_e32 v144, 16, v235
	v_and_b32_e32 v145, 0xffff0000, v235
	v_pk_mul_f32 v[4:5], v[4:5], v[162:163]
	v_pk_mul_f32 v[6:7], v[6:7], v[164:165]
	v_pk_mul_f32 v[0:1], v[0:1], v[158:159]
	v_pk_mul_f32 v[2:3], v[2:3], v[144:145]
	v_cvt_pk_bf16_f32 v232, v4, v5
	v_cvt_pk_bf16_f32 v233, v6, v7
	v_cvt_pk_bf16_f32 v234, v0, v1
	v_cvt_pk_bf16_f32 v235, v2, v3
	v_add_u32_e32 v156, 0x2c100, v155
	global_store_dwordx4 v156, v[232:235], s[100:101]
	s_andn2_b64 vcc, exec, s[4:5]
	s_mov_b64 s[4:5], -1
	s_cbranch_vccnz .LBB0_701
	s_andn2_b64 vcc, exec, s[8:9]
	s_cbranch_vccnz .LBB0_700
	s_barrier
	s_branch .LBB0_700
